# test: P1 output H0 placed in the (then unused) Y region of the workspace instead of the H region - probes whether first-touch placement relative to what the memory-side cache holds at launch matters
# speedup vs baseline: 1.0065x; 1.0065x over previous
; __device__ __forceinline__ unsigned cvt_pk_bf16(float lo, float hi) { unsigned r; asm volatile("v_cvt_pk_bf16_f32 %0, %1, %2" : "=v"(r) : "v"(lo), "v"(hi)); return r; }
; __device__ __forceinline__ void load_row_f32(const float* p, int lane, f32x4 (&v)[8]) {
; #pragma unroll
;     for (int j = 0; j < 8; ++j) v[j] = *(const f32x4*)(p + 4 * lane + 256 * j);
; }
; __device__ __forceinline__ float sumsq8(const f32x4 (&v)[8]) {
;     float s = 0.f;
; #pragma unroll
;     for (int j = 0; j < 8; ++j) s += (v[j][0] * v[j][0] + v[j][1] * v[j][1]) + (v[j][2] * v[j][2] + v[j][3] * v[j][3]);
;     return wave_sum(s);
; }
; __device__ __forceinline__ void modulate_store(const f32x4 (&v)[8], float rstd, const float* pn, const float* modr, bf16_t* orow, int lane) {
; #pragma unroll
;     for (int j = 0; j < 8; ++j) { const int col = 4 * lane + 256 * j;
;         const f32x4 g = *(const f32x4*)(pn + col), sh = *(const f32x4*)(modr + col), sc = *(const f32x4*)(modr + DM + col);
;         const f32x4 hh = v[j] * rstd * g * (sc + 1.f) + sh;
;         u32x2 w; w.x = cvt_pk_bf16(hh[0], hh[1]); w.y = cvt_pk_bf16(hh[2], hh[3]);
;         *(u32x2*)(orow + col) = w; }
; }
; __global__ void __launch_bounds__(NWAVES * 64, 2) mk_fwd(Args args) {
;     ...
;         for (int row0 = F.gw * 3; row0 < MT; row0 += F.NGW * 3) {
;             f32x4 v[3][8];
; #pragma unroll
;             for (int q = 0; q < 3; ++q) { const int row = row0 + q; const float* src = row < ML ? x + (size_t)row * DM : ctx + (size_t)(row - ML) * DM; load_row_f32(src, F.lane, v[q]); }
; #pragma unroll
;             for (int q = 0; q < 3; ++q) { const int row = row0 + q; const int r = row < ML ? row / SEQ : 8;
;                 const float rstd = __builtin_amdgcn_rsqf(sumsq8(v[q]) * (1.f / DM) + EPS);
;                 modulate_store(v[q], rstd, pre_norm, mod + (size_t)r * 6144, H + (size_t)row * DM, F.lane); }
;         }
.Lp1_np0:
	s_add_i32 s4, s6, 1
	s_cmp_lt_u32 s4, 0x4000
	s_cselect_b32 s10, s68, s72
	s_cselect_b32 s11, s69, s73
	s_cselect_b32 s5, 0, 0x4000
	s_sub_i32 s5, s4, s5
	s_lshl_b32 s5, s5, 13
	s_add_u32 s10, s10, s5
	s_addc_u32 s11, s11, 0
	global_load_dwordx4 v[32:35], v128, s[10:11] offset:0 nt
	global_load_dwordx4 v[36:39], v128, s[10:11] offset:1024 nt
	global_load_dwordx4 v[40:43], v128, s[10:11] offset:2048 nt
	global_load_dwordx4 v[44:47], v128, s[10:11] offset:3072 nt
	global_load_dwordx4 v[48:51], v129, s[10:11] offset:0 nt
	global_load_dwordx4 v[52:55], v129, s[10:11] offset:1024 nt
	global_load_dwordx4 v[56:59], v129, s[10:11] offset:2048 nt
	global_load_dwordx4 v[60:63], v129, s[10:11] offset:3072 nt
	s_waitcnt vmcnt(8)
	v_mul_f32_e32 v140, v0, v0
	v_mul_f32_e32 v141, v1, v1
	v_fmac_f32_e32 v140, v2, v2
	v_fmac_f32_e32 v141, v3, v3
	v_fmac_f32_e32 v140, v4, v4
	v_fmac_f32_e32 v141, v5, v5
	v_fmac_f32_e32 v140, v6, v6
	v_fmac_f32_e32 v141, v7, v7
	v_fmac_f32_e32 v140, v8, v8
	v_fmac_f32_e32 v141, v9, v9
	v_fmac_f32_e32 v140, v10, v10
	v_fmac_f32_e32 v141, v11, v11
	v_fmac_f32_e32 v140, v12, v12
	v_fmac_f32_e32 v141, v13, v13
	v_fmac_f32_e32 v140, v14, v14
	v_fmac_f32_e32 v141, v15, v15
	v_fmac_f32_e32 v140, v16, v16
	v_fmac_f32_e32 v141, v17, v17
	v_fmac_f32_e32 v140, v18, v18
	v_fmac_f32_e32 v141, v19, v19
	v_fmac_f32_e32 v140, v20, v20
	v_fmac_f32_e32 v141, v21, v21
	v_fmac_f32_e32 v140, v22, v22
	v_fmac_f32_e32 v141, v23, v23
	v_fmac_f32_e32 v140, v24, v24
	v_fmac_f32_e32 v141, v25, v25
	v_fmac_f32_e32 v140, v26, v26
	v_fmac_f32_e32 v141, v27, v27
	v_fmac_f32_e32 v140, v28, v28
	v_fmac_f32_e32 v141, v29, v29
	v_fmac_f32_e32 v140, v30, v30
	v_fmac_f32_e32 v141, v31, v31
	v_add_f32_e32 v140, v140, v141
	s_nop 1
	v_add_f32_dpp v142, v140, v140 quad_perm:[1,0,3,2] row_mask:0xf bank_mask:0xf
	s_nop 1
	v_add_f32_dpp v142, v142, v142 quad_perm:[2,3,0,1] row_mask:0xf bank_mask:0xf
	s_nop 1
	v_add_f32_dpp v142, v142, v142 row_half_mirror row_mask:0xf bank_mask:0xf
	s_nop 1
	v_add_f32_dpp v142, v142, v142 row_mirror row_mask:0xf bank_mask:0xf
	s_nop 1
	v_readlane_b32 s20, v142, 0
	v_readlane_b32 s21, v142, 16
	v_readlane_b32 s22, v142, 32
	v_readlane_b32 s23, v142, 48
	s_nop 1
	v_mov_b32_e32 v143, s20
	v_add_f32_e32 v143, s21, v143
	v_add_f32_e32 v143, s22, v143
	v_add_f32_e32 v143, s23, v143
	v_fmamk_f32 v143, v143, 0x3a000000, v131
	v_rsq_f32_e32 v143, v143
	s_nop 0
	s_add_i32 s4, s6, 0
	s_lshl_b32 s5, s4, 12
	s_add_u32 s14, s84, s5
	s_addc_u32 s15, s85, 0
	s_add_u32 s14, s14, 0x11800000
	s_addc_u32 s15, s15, 0
	v_mul_f32_e32 v136, v143, v0
	v_mul_f32_e32 v137, v143, v1
	v_mul_f32_e32 v138, v143, v2
	v_mul_f32_e32 v139, v143, v3
	v_fma_f32 v136, v136, v64, v96
	v_fma_f32 v137, v137, v65, v97
	v_fma_f32 v138, v138, v66, v98
	v_fma_f32 v139, v139, v67, v99
	v_cvt_pk_bf16_f32 v132, v136, v137
	v_cvt_pk_bf16_f32 v133, v138, v139
	global_store_dwordx2 v130, v[132:133], s[14:15] offset:0
	v_mul_f32_e32 v136, v143, v4
	v_mul_f32_e32 v137, v143, v5
	v_mul_f32_e32 v138, v143, v6
	v_mul_f32_e32 v139, v143, v7
	v_fma_f32 v136, v136, v68, v100
	v_fma_f32 v137, v137, v69, v101
	v_fma_f32 v138, v138, v70, v102
	v_fma_f32 v139, v139, v71, v103
	v_cvt_pk_bf16_f32 v134, v136, v137
	v_cvt_pk_bf16_f32 v135, v138, v139
	global_store_dwordx2 v130, v[134:135], s[14:15] offset:512
	v_mul_f32_e32 v136, v143, v8
	v_mul_f32_e32 v137, v143, v9
	v_mul_f32_e32 v138, v143, v10
	v_mul_f32_e32 v139, v143, v11
	v_fma_f32 v136, v136, v72, v104
	v_fma_f32 v137, v137, v73, v105
	v_fma_f32 v138, v138, v74, v106
	v_fma_f32 v139, v139, v75, v107
	v_cvt_pk_bf16_f32 v132, v136, v137
	v_cvt_pk_bf16_f32 v133, v138, v139
	global_store_dwordx2 v130, v[132:133], s[14:15] offset:1024
	v_mul_f32_e32 v136, v143, v12
	v_mul_f32_e32 v137, v143, v13
	v_mul_f32_e32 v138, v143, v14
	v_mul_f32_e32 v139, v143, v15
	v_fma_f32 v136, v136, v76, v108
	v_fma_f32 v137, v137, v77, v109
	v_fma_f32 v138, v138, v78, v110
	v_fma_f32 v139, v139, v79, v111
	v_cvt_pk_bf16_f32 v134, v136, v137
	v_cvt_pk_bf16_f32 v135, v138, v139
	global_store_dwordx2 v130, v[134:135], s[14:15] offset:1536
	v_mul_f32_e32 v136, v143, v16
	v_mul_f32_e32 v137, v143, v17
	v_mul_f32_e32 v138, v143, v18
	v_mul_f32_e32 v139, v143, v19
	v_fma_f32 v136, v136, v80, v112
	v_fma_f32 v137, v137, v81, v113
	v_fma_f32 v138, v138, v82, v114
	v_fma_f32 v139, v139, v83, v115
	v_cvt_pk_bf16_f32 v132, v136, v137
	v_cvt_pk_bf16_f32 v133, v138, v139
	global_store_dwordx2 v130, v[132:133], s[14:15] offset:2048
	v_mul_f32_e32 v136, v143, v20
	v_mul_f32_e32 v137, v143, v21
	v_mul_f32_e32 v138, v143, v22
	v_mul_f32_e32 v139, v143, v23
	v_fma_f32 v136, v136, v84, v116
	v_fma_f32 v137, v137, v85, v117
	v_fma_f32 v138, v138, v86, v118
	v_fma_f32 v139, v139, v87, v119
	v_cvt_pk_bf16_f32 v134, v136, v137
	v_cvt_pk_bf16_f32 v135, v138, v139
	global_store_dwordx2 v130, v[134:135], s[14:15] offset:2560
	v_mul_f32_e32 v136, v143, v24
	v_mul_f32_e32 v137, v143, v25
	v_mul_f32_e32 v138, v143, v26
	v_mul_f32_e32 v139, v143, v27
	v_fma_f32 v136, v136, v88, v120
	v_fma_f32 v137, v137, v89, v121
	v_fma_f32 v138, v138, v90, v122
	v_fma_f32 v139, v139, v91, v123
	v_cvt_pk_bf16_f32 v132, v136, v137
	v_cvt_pk_bf16_f32 v133, v138, v139
	global_store_dwordx2 v130, v[132:133], s[14:15] offset:3072
	v_mul_f32_e32 v136, v143, v28
	v_mul_f32_e32 v137, v143, v29
	v_mul_f32_e32 v138, v143, v30
	v_mul_f32_e32 v139, v143, v31
	v_fma_f32 v136, v136, v92, v124
	v_fma_f32 v137, v137, v93, v125
	v_fma_f32 v138, v138, v94, v126
	v_fma_f32 v139, v139, v95, v127
	v_cvt_pk_bf16_f32 v134, v136, v137
	v_cvt_pk_bf16_f32 v135, v138, v139
	global_store_dwordx2 v130, v[134:135], s[14:15] offset:3584
	s_add_i32 s4, s6, 2
	s_cmp_lt_u32 s4, 0x4000
	s_cselect_b32 s10, s68, s72
	s_cselect_b32 s11, s69, s73
	s_cselect_b32 s5, 0, 0x4000
	s_sub_i32 s5, s4, s5
	s_lshl_b32 s5, s5, 13
	s_add_u32 s10, s10, s5
	s_addc_u32 s11, s11, 0
	global_load_dwordx4 v[0:3], v128, s[10:11] offset:0 nt
	global_load_dwordx4 v[4:7], v128, s[10:11] offset:1024 nt
	global_load_dwordx4 v[8:11], v128, s[10:11] offset:2048 nt
	global_load_dwordx4 v[12:15], v128, s[10:11] offset:3072 nt
	global_load_dwordx4 v[16:19], v129, s[10:11] offset:0 nt
	global_load_dwordx4 v[20:23], v129, s[10:11] offset:1024 nt
	global_load_dwordx4 v[24:27], v129, s[10:11] offset:2048 nt
	global_load_dwordx4 v[28:31], v129, s[10:11] offset:3072 nt
	s_add_i32 s4, s6, 1
	s_add_i32 s4, s6, 1
	s_lshr_b32 s8, s4, 11
	s_cmp_lt_u32 s4, 0x4000
	s_cselect_b32 s8, s8, 8
	s_cmp_eq_u32 s8, s7
	s_cbranch_scc1 .Lp1_np1
; __device__ __forceinline__ unsigned cvt_pk_bf16(float lo, float hi) { unsigned r; asm volatile("v_cvt_pk_bf16_f32 %0, %1, %2" : "=v"(r) : "v"(lo), "v"(hi)); return r; }
; __device__ __forceinline__ void modulate_store(const f32x4 (&v)[8], float rstd, const float* pn, const float* modr, bf16_t* orow, int lane) {
; #pragma unroll
;     for (int j = 0; j < 8; ++j) { const int col = 4 * lane + 256 * j;
;         const f32x4 g = *(const f32x4*)(pn + col), sh = *(const f32x4*)(modr + col), sc = *(const f32x4*)(modr + DM + col);
;         const f32x4 hh = v[j] * rstd * g * (sc + 1.f) + sh;
;         u32x2 w; w.x = cvt_pk_bf16(hh[0], hh[1]); w.y = cvt_pk_bf16(hh[2], hh[3]);
;         *(u32x2*)(orow + col) = w; }
; }
; __global__ void __launch_bounds__(NWAVES * 64, 2) mk_fwd(Args args) {
;     ...
;         for (int row0 = F.gw * 3; row0 < MT; row0 += F.NGW * 3) {
;             f32x4 v[3][8];
; #pragma unroll
;             for (int q = 0; q < 3; ++q) { const int row = row0 + q; const float* src = row < ML ? x + (size_t)row * DM : ctx + (size_t)(row - ML) * DM; load_row_f32(src, F.lane, v[q]); }
; #pragma unroll
;             for (int q = 0; q < 3; ++q) { const int row = row0 + q; const int r = row < ML ? row / SEQ : 8;
;                 const float rstd = __builtin_amdgcn_rsqf(sumsq8(v[q]) * (1.f / DM) + EPS);
;                 modulate_store(v[q], rstd, pre_norm, mod + (size_t)r * 6144, H + (size_t)row * DM, F.lane); }
;         }
	s_mov_b32 s7, s8
	s_add_i32 s5, s8, 0
	s_mul_i32 s5, s5, 0x6000
	s_add_u32 s24, s84, s5
	s_addc_u32 s25, s85, 0
	s_add_u32 s24, s24, 0x2000
	s_addc_u32 s25, s25, 0
	s_add_i32 s5, s8, 0
	s_mul_i32 s5, s5, 0x6000
	s_add_u32 s16, s84, s5
	s_addc_u32 s17, s85, 0
	s_add_u32 s18, s80, 0x0
	s_addc_u32 s19, s81, 0
	global_load_dwordx4 v[64:67], v128, s[18:19] offset:0
	global_load_dwordx4 v[96:99], v128, s[16:17] offset:0
	global_load_dwordx4 v[68:71], v128, s[18:19] offset:1024
	global_load_dwordx4 v[100:103], v128, s[16:17] offset:1024
	global_load_dwordx4 v[72:75], v128, s[18:19] offset:2048
	global_load_dwordx4 v[104:107], v128, s[16:17] offset:2048
	global_load_dwordx4 v[76:79], v128, s[18:19] offset:3072
	global_load_dwordx4 v[108:111], v128, s[16:17] offset:3072
	global_load_dwordx4 v[80:83], v129, s[18:19] offset:0
	global_load_dwordx4 v[112:115], v129, s[16:17] offset:0
	global_load_dwordx4 v[84:87], v129, s[18:19] offset:1024
	global_load_dwordx4 v[116:119], v129, s[16:17] offset:1024
	global_load_dwordx4 v[88:91], v129, s[18:19] offset:2048
	global_load_dwordx4 v[120:123], v129, s[16:17] offset:2048
	global_load_dwordx4 v[92:95], v129, s[18:19] offset:3072
	global_load_dwordx4 v[124:127], v129, s[16:17] offset:3072
	global_load_dwordx4 v[136:139], v128, s[24:25] offset:0
	s_waitcnt vmcnt(0)
	v_add_f32_e32 v136, 1.0, v136
	v_add_f32_e32 v137, 1.0, v137
	v_add_f32_e32 v138, 1.0, v138
	v_add_f32_e32 v139, 1.0, v139
	v_mul_f32_e32 v64, v64, v136
	v_mul_f32_e32 v65, v65, v137
	v_mul_f32_e32 v66, v66, v138
	v_mul_f32_e32 v67, v67, v139
	global_load_dwordx4 v[136:139], v128, s[24:25] offset:1024
	s_waitcnt vmcnt(0)
	v_add_f32_e32 v136, 1.0, v136
	v_add_f32_e32 v137, 1.0, v137
	v_add_f32_e32 v138, 1.0, v138
	v_add_f32_e32 v139, 1.0, v139
	v_mul_f32_e32 v68, v68, v136
	v_mul_f32_e32 v69, v69, v137
	v_mul_f32_e32 v70, v70, v138
	v_mul_f32_e32 v71, v71, v139
	global_load_dwordx4 v[136:139], v128, s[24:25] offset:2048
	s_waitcnt vmcnt(0)
	v_add_f32_e32 v136, 1.0, v136
	v_add_f32_e32 v137, 1.0, v137
	v_add_f32_e32 v138, 1.0, v138
	v_add_f32_e32 v139, 1.0, v139
	v_mul_f32_e32 v72, v72, v136
	v_mul_f32_e32 v73, v73, v137
	v_mul_f32_e32 v74, v74, v138
	v_mul_f32_e32 v75, v75, v139
	global_load_dwordx4 v[136:139], v128, s[24:25] offset:3072
	s_waitcnt vmcnt(0)
	v_add_f32_e32 v136, 1.0, v136
	v_add_f32_e32 v137, 1.0, v137
	v_add_f32_e32 v138, 1.0, v138
	v_add_f32_e32 v139, 1.0, v139
	v_mul_f32_e32 v76, v76, v136
	v_mul_f32_e32 v77, v77, v137
	v_mul_f32_e32 v78, v78, v138
	v_mul_f32_e32 v79, v79, v139
	global_load_dwordx4 v[136:139], v129, s[24:25] offset:0
	s_waitcnt vmcnt(0)
	v_add_f32_e32 v136, 1.0, v136
	v_add_f32_e32 v137, 1.0, v137
	v_add_f32_e32 v138, 1.0, v138
	v_add_f32_e32 v139, 1.0, v139
	v_mul_f32_e32 v80, v80, v136
	v_mul_f32_e32 v81, v81, v137
	v_mul_f32_e32 v82, v82, v138
	v_mul_f32_e32 v83, v83, v139
	global_load_dwordx4 v[136:139], v129, s[24:25] offset:1024
	s_waitcnt vmcnt(0)
	v_add_f32_e32 v136, 1.0, v136
	v_add_f32_e32 v137, 1.0, v137
	v_add_f32_e32 v138, 1.0, v138
	v_add_f32_e32 v139, 1.0, v139
	v_mul_f32_e32 v84, v84, v136
	v_mul_f32_e32 v85, v85, v137
	v_mul_f32_e32 v86, v86, v138
	v_mul_f32_e32 v87, v87, v139
	global_load_dwordx4 v[136:139], v129, s[24:25] offset:2048
	s_waitcnt vmcnt(0)
	v_add_f32_e32 v136, 1.0, v136
	v_add_f32_e32 v137, 1.0, v137
	v_add_f32_e32 v138, 1.0, v138
	v_add_f32_e32 v139, 1.0, v139
	v_mul_f32_e32 v88, v88, v136
	v_mul_f32_e32 v89, v89, v137
	v_mul_f32_e32 v90, v90, v138
	v_mul_f32_e32 v91, v91, v139
	global_load_dwordx4 v[136:139], v129, s[24:25] offset:3072
	s_waitcnt vmcnt(0)
	v_add_f32_e32 v136, 1.0, v136
	v_add_f32_e32 v137, 1.0, v137
	v_add_f32_e32 v138, 1.0, v138
	v_add_f32_e32 v139, 1.0, v139
	v_mul_f32_e32 v92, v92, v136
	v_mul_f32_e32 v93, v93, v137
	v_mul_f32_e32 v94, v94, v138
	v_mul_f32_e32 v95, v95, v139
.Lp1_np1:
	s_waitcnt vmcnt(16)
	v_mul_f32_e32 v140, v32, v32
	v_mul_f32_e32 v141, v33, v33
	v_fmac_f32_e32 v140, v34, v34
	v_fmac_f32_e32 v141, v35, v35
	v_fmac_f32_e32 v140, v36, v36
	v_fmac_f32_e32 v141, v37, v37
	v_fmac_f32_e32 v140, v38, v38
	v_fmac_f32_e32 v141, v39, v39
	v_fmac_f32_e32 v140, v40, v40
	v_fmac_f32_e32 v141, v41, v41
	v_fmac_f32_e32 v140, v42, v42
	v_fmac_f32_e32 v141, v43, v43
	v_fmac_f32_e32 v140, v44, v44
	v_fmac_f32_e32 v141, v45, v45
	v_fmac_f32_e32 v140, v46, v46
	v_fmac_f32_e32 v141, v47, v47
	v_fmac_f32_e32 v140, v48, v48
	v_fmac_f32_e32 v141, v49, v49
	v_fmac_f32_e32 v140, v50, v50
	v_fmac_f32_e32 v141, v51, v51
	v_fmac_f32_e32 v140, v52, v52
	v_fmac_f32_e32 v141, v53, v53
	v_fmac_f32_e32 v140, v54, v54
	v_fmac_f32_e32 v141, v55, v55
	v_fmac_f32_e32 v140, v56, v56
	v_fmac_f32_e32 v141, v57, v57
	v_fmac_f32_e32 v140, v58, v58
	v_fmac_f32_e32 v141, v59, v59
	v_fmac_f32_e32 v140, v60, v60
	v_fmac_f32_e32 v141, v61, v61
	v_fmac_f32_e32 v140, v62, v62
	v_fmac_f32_e32 v141, v63, v63
	v_add_f32_e32 v140, v140, v141
	s_nop 1
	v_add_f32_dpp v142, v140, v140 quad_perm:[1,0,3,2] row_mask:0xf bank_mask:0xf
	s_nop 1
	v_add_f32_dpp v142, v142, v142 quad_perm:[2,3,0,1] row_mask:0xf bank_mask:0xf
	s_nop 1
	v_add_f32_dpp v142, v142, v142 row_half_mirror row_mask:0xf bank_mask:0xf
	s_nop 1
	v_add_f32_dpp v142, v142, v142 row_mirror row_mask:0xf bank_mask:0xf
	s_nop 1
	v_readlane_b32 s20, v142, 0
	v_readlane_b32 s21, v142, 16
	v_readlane_b32 s22, v142, 32
	v_readlane_b32 s23, v142, 48
	s_nop 1
	v_mov_b32_e32 v143, s20
	v_add_f32_e32 v143, s21, v143
	v_add_f32_e32 v143, s22, v143
	v_add_f32_e32 v143, s23, v143
	v_fmamk_f32 v143, v143, 0x3a000000, v131
	v_rsq_f32_e32 v143, v143
	s_nop 0
	s_add_i32 s4, s6, 1
	s_lshl_b32 s5, s4, 12
	s_add_u32 s14, s84, s5
	s_addc_u32 s15, s85, 0
; __device__ __forceinline__ unsigned cvt_pk_bf16(float lo, float hi) { unsigned r; asm volatile("v_cvt_pk_bf16_f32 %0, %1, %2" : "=v"(r) : "v"(lo), "v"(hi)); return r; }
; __device__ __forceinline__ void modulate_store(const f32x4 (&v)[8], float rstd, const float* pn, const float* modr, bf16_t* orow, int lane) {
; #pragma unroll
;     for (int j = 0; j < 8; ++j) { const int col = 4 * lane + 256 * j;
;         const f32x4 g = *(const f32x4*)(pn + col), sh = *(const f32x4*)(modr + col), sc = *(const f32x4*)(modr + DM + col);
;         const f32x4 hh = v[j] * rstd * g * (sc + 1.f) + sh;
;         u32x2 w; w.x = cvt_pk_bf16(hh[0], hh[1]); w.y = cvt_pk_bf16(hh[2], hh[3]);
;         *(u32x2*)(orow + col) = w; }
; }
; __global__ void __launch_bounds__(NWAVES * 64, 2) mk_fwd(Args args) {
;     ...
;         for (int row0 = F.gw * 3; row0 < MT; row0 += F.NGW * 3) {
;             f32x4 v[3][8];
; #pragma unroll
;             for (int q = 0; q < 3; ++q) { const int row = row0 + q; const float* src = row < ML ? x + (size_t)row * DM : ctx + (size_t)(row - ML) * DM; load_row_f32(src, F.lane, v[q]); }
; #pragma unroll
;             for (int q = 0; q < 3; ++q) { const int row = row0 + q; const int r = row < ML ? row / SEQ : 8;
;                 const float rstd = __builtin_amdgcn_rsqf(sumsq8(v[q]) * (1.f / DM) + EPS);
;                 modulate_store(v[q], rstd, pre_norm, mod + (size_t)r * 6144, H + (size_t)row * DM, F.lane); }
;         }
	s_add_u32 s14, s14, 0x11800000
	s_addc_u32 s15, s15, 0
	v_mul_f32_e32 v136, v143, v32
	v_mul_f32_e32 v137, v143, v33
	v_mul_f32_e32 v138, v143, v34
	v_mul_f32_e32 v139, v143, v35
	v_fma_f32 v136, v136, v64, v96
	v_fma_f32 v137, v137, v65, v97
	v_fma_f32 v138, v138, v66, v98
	v_fma_f32 v139, v139, v67, v99
	v_cvt_pk_bf16_f32 v132, v136, v137
	v_cvt_pk_bf16_f32 v133, v138, v139
	global_store_dwordx2 v130, v[132:133], s[14:15] offset:0
	v_mul_f32_e32 v136, v143, v36
	v_mul_f32_e32 v137, v143, v37
	v_mul_f32_e32 v138, v143, v38
	v_mul_f32_e32 v139, v143, v39
	v_fma_f32 v136, v136, v68, v100
	v_fma_f32 v137, v137, v69, v101
	v_fma_f32 v138, v138, v70, v102
	v_fma_f32 v139, v139, v71, v103
	v_cvt_pk_bf16_f32 v134, v136, v137
	v_cvt_pk_bf16_f32 v135, v138, v139
	global_store_dwordx2 v130, v[134:135], s[14:15] offset:512
	v_mul_f32_e32 v136, v143, v40
	v_mul_f32_e32 v137, v143, v41
	v_mul_f32_e32 v138, v143, v42
	v_mul_f32_e32 v139, v143, v43
	v_fma_f32 v136, v136, v72, v104
	v_fma_f32 v137, v137, v73, v105
	v_fma_f32 v138, v138, v74, v106
	v_fma_f32 v139, v139, v75, v107
	v_cvt_pk_bf16_f32 v132, v136, v137
	v_cvt_pk_bf16_f32 v133, v138, v139
	global_store_dwordx2 v130, v[132:133], s[14:15] offset:1024
	v_mul_f32_e32 v136, v143, v44
	v_mul_f32_e32 v137, v143, v45
	v_mul_f32_e32 v138, v143, v46
	v_mul_f32_e32 v139, v143, v47
	v_fma_f32 v136, v136, v76, v108
	v_fma_f32 v137, v137, v77, v109
	v_fma_f32 v138, v138, v78, v110
	v_fma_f32 v139, v139, v79, v111
	v_cvt_pk_bf16_f32 v134, v136, v137
	v_cvt_pk_bf16_f32 v135, v138, v139
	global_store_dwordx2 v130, v[134:135], s[14:15] offset:1536
	v_mul_f32_e32 v136, v143, v48
	v_mul_f32_e32 v137, v143, v49
	v_mul_f32_e32 v138, v143, v50
	v_mul_f32_e32 v139, v143, v51
	v_fma_f32 v136, v136, v80, v112
	v_fma_f32 v137, v137, v81, v113
	v_fma_f32 v138, v138, v82, v114
	v_fma_f32 v139, v139, v83, v115
	v_cvt_pk_bf16_f32 v132, v136, v137
	v_cvt_pk_bf16_f32 v133, v138, v139
	global_store_dwordx2 v130, v[132:133], s[14:15] offset:2048
	v_mul_f32_e32 v136, v143, v52
	v_mul_f32_e32 v137, v143, v53
	v_mul_f32_e32 v138, v143, v54
	v_mul_f32_e32 v139, v143, v55
	v_fma_f32 v136, v136, v84, v116
	v_fma_f32 v137, v137, v85, v117
	v_fma_f32 v138, v138, v86, v118
	v_fma_f32 v139, v139, v87, v119
	v_cvt_pk_bf16_f32 v134, v136, v137
	v_cvt_pk_bf16_f32 v135, v138, v139
	global_store_dwordx2 v130, v[134:135], s[14:15] offset:2560
	v_mul_f32_e32 v136, v143, v56
	v_mul_f32_e32 v137, v143, v57
	v_mul_f32_e32 v138, v143, v58
	v_mul_f32_e32 v139, v143, v59
	v_fma_f32 v136, v136, v88, v120
	v_fma_f32 v137, v137, v89, v121
	v_fma_f32 v138, v138, v90, v122
	v_fma_f32 v139, v139, v91, v123
	v_cvt_pk_bf16_f32 v132, v136, v137
	v_cvt_pk_bf16_f32 v133, v138, v139
	global_store_dwordx2 v130, v[132:133], s[14:15] offset:3072
	v_mul_f32_e32 v136, v143, v60
	v_mul_f32_e32 v137, v143, v61
	v_mul_f32_e32 v138, v143, v62
	v_mul_f32_e32 v139, v143, v63
	v_fma_f32 v136, v136, v92, v124
	v_fma_f32 v137, v137, v93, v125
	v_fma_f32 v138, v138, v94, v126
	v_fma_f32 v139, v139, v95, v127
	v_cvt_pk_bf16_f32 v134, v136, v137
	v_cvt_pk_bf16_f32 v135, v138, v139
	global_store_dwordx2 v130, v[134:135], s[14:15] offset:3584
	s_add_i32 s4, s6, 3
	s_cmp_lt_u32 s4, 0x4000
	s_cselect_b32 s10, s68, s72
	s_cselect_b32 s11, s69, s73
	s_cselect_b32 s5, 0, 0x4000
	s_sub_i32 s5, s4, s5
	s_lshl_b32 s5, s5, 13
	s_add_u32 s10, s10, s5
	s_addc_u32 s11, s11, 0
	global_load_dwordx4 v[32:35], v128, s[10:11] offset:0 nt
	global_load_dwordx4 v[36:39], v128, s[10:11] offset:1024 nt
	global_load_dwordx4 v[40:43], v128, s[10:11] offset:2048 nt
	global_load_dwordx4 v[44:47], v128, s[10:11] offset:3072 nt
	global_load_dwordx4 v[48:51], v129, s[10:11] offset:0 nt
	global_load_dwordx4 v[52:55], v129, s[10:11] offset:1024 nt
	global_load_dwordx4 v[56:59], v129, s[10:11] offset:2048 nt
	global_load_dwordx4 v[60:63], v129, s[10:11] offset:3072 nt
	s_add_i32 s4, s6, 2
	s_add_i32 s4, s6, 2
	s_lshr_b32 s8, s4, 11
	s_cmp_lt_u32 s4, 0x4000
	s_cselect_b32 s8, s8, 8
	s_cmp_eq_u32 s8, s7
	s_cbranch_scc1 .Lp1_np2
	s_mov_b32 s7, s8
	s_add_i32 s5, s8, 0
	s_mul_i32 s5, s5, 0x6000
	s_add_u32 s24, s84, s5
	s_addc_u32 s25, s85, 0
	s_add_u32 s24, s24, 0x2000
	s_addc_u32 s25, s25, 0
	s_add_i32 s5, s8, 0
	s_mul_i32 s5, s5, 0x6000
	s_add_u32 s16, s84, s5
	s_addc_u32 s17, s85, 0
	s_add_u32 s18, s80, 0x0
	s_addc_u32 s19, s81, 0
	global_load_dwordx4 v[64:67], v128, s[18:19] offset:0
	global_load_dwordx4 v[96:99], v128, s[16:17] offset:0
	global_load_dwordx4 v[68:71], v128, s[18:19] offset:1024
	global_load_dwordx4 v[100:103], v128, s[16:17] offset:1024
	global_load_dwordx4 v[72:75], v128, s[18:19] offset:2048
	global_load_dwordx4 v[104:107], v128, s[16:17] offset:2048
	global_load_dwordx4 v[76:79], v128, s[18:19] offset:3072
	global_load_dwordx4 v[108:111], v128, s[16:17] offset:3072
	global_load_dwordx4 v[80:83], v129, s[18:19] offset:0
	global_load_dwordx4 v[112:115], v129, s[16:17] offset:0
	global_load_dwordx4 v[84:87], v129, s[18:19] offset:1024
	global_load_dwordx4 v[116:119], v129, s[16:17] offset:1024
	global_load_dwordx4 v[88:91], v129, s[18:19] offset:2048
	global_load_dwordx4 v[120:123], v129, s[16:17] offset:2048
	global_load_dwordx4 v[92:95], v129, s[18:19] offset:3072
	global_load_dwordx4 v[124:127], v129, s[16:17] offset:3072
	global_load_dwordx4 v[136:139], v128, s[24:25] offset:0
	s_waitcnt vmcnt(0)
	v_add_f32_e32 v136, 1.0, v136
	v_add_f32_e32 v137, 1.0, v137
	v_add_f32_e32 v138, 1.0, v138
	v_add_f32_e32 v139, 1.0, v139
	v_mul_f32_e32 v64, v64, v136
	v_mul_f32_e32 v65, v65, v137
	v_mul_f32_e32 v66, v66, v138
	v_mul_f32_e32 v67, v67, v139
	global_load_dwordx4 v[136:139], v128, s[24:25] offset:1024
	s_waitcnt vmcnt(0)
; __device__ __forceinline__ unsigned cvt_pk_bf16(float lo, float hi) { unsigned r; asm volatile("v_cvt_pk_bf16_f32 %0, %1, %2" : "=v"(r) : "v"(lo), "v"(hi)); return r; }
; __device__ __forceinline__ void modulate_store(const f32x4 (&v)[8], float rstd, const float* pn, const float* modr, bf16_t* orow, int lane) {
; #pragma unroll
;     for (int j = 0; j < 8; ++j) { const int col = 4 * lane + 256 * j;
;         const f32x4 g = *(const f32x4*)(pn + col), sh = *(const f32x4*)(modr + col), sc = *(const f32x4*)(modr + DM + col);
;         const f32x4 hh = v[j] * rstd * g * (sc + 1.f) + sh;
;         u32x2 w; w.x = cvt_pk_bf16(hh[0], hh[1]); w.y = cvt_pk_bf16(hh[2], hh[3]);
;         *(u32x2*)(orow + col) = w; }
; }
; __global__ void __launch_bounds__(NWAVES * 64, 2) mk_fwd(Args args) {
;     ...
;         for (int row0 = F.gw * 3; row0 < MT; row0 += F.NGW * 3) {
;             f32x4 v[3][8];
; #pragma unroll
;             for (int q = 0; q < 3; ++q) { const int row = row0 + q; const float* src = row < ML ? x + (size_t)row * DM : ctx + (size_t)(row - ML) * DM; load_row_f32(src, F.lane, v[q]); }
; #pragma unroll
;             for (int q = 0; q < 3; ++q) { const int row = row0 + q; const int r = row < ML ? row / SEQ : 8;
;                 const float rstd = __builtin_amdgcn_rsqf(sumsq8(v[q]) * (1.f / DM) + EPS);
;                 modulate_store(v[q], rstd, pre_norm, mod + (size_t)r * 6144, H + (size_t)row * DM, F.lane); }
;         }
	v_add_f32_e32 v136, 1.0, v136
	v_add_f32_e32 v137, 1.0, v137
	v_add_f32_e32 v138, 1.0, v138
	v_add_f32_e32 v139, 1.0, v139
	v_mul_f32_e32 v68, v68, v136
	v_mul_f32_e32 v69, v69, v137
	v_mul_f32_e32 v70, v70, v138
	v_mul_f32_e32 v71, v71, v139
	global_load_dwordx4 v[136:139], v128, s[24:25] offset:2048
	s_waitcnt vmcnt(0)
	v_add_f32_e32 v136, 1.0, v136
	v_add_f32_e32 v137, 1.0, v137
	v_add_f32_e32 v138, 1.0, v138
	v_add_f32_e32 v139, 1.0, v139
	v_mul_f32_e32 v72, v72, v136
	v_mul_f32_e32 v73, v73, v137
	v_mul_f32_e32 v74, v74, v138
	v_mul_f32_e32 v75, v75, v139
	global_load_dwordx4 v[136:139], v128, s[24:25] offset:3072
	s_waitcnt vmcnt(0)
	v_add_f32_e32 v136, 1.0, v136
	v_add_f32_e32 v137, 1.0, v137
	v_add_f32_e32 v138, 1.0, v138
	v_add_f32_e32 v139, 1.0, v139
	v_mul_f32_e32 v76, v76, v136
	v_mul_f32_e32 v77, v77, v137
	v_mul_f32_e32 v78, v78, v138
	v_mul_f32_e32 v79, v79, v139
	global_load_dwordx4 v[136:139], v129, s[24:25] offset:0
	s_waitcnt vmcnt(0)
	v_add_f32_e32 v136, 1.0, v136
	v_add_f32_e32 v137, 1.0, v137
	v_add_f32_e32 v138, 1.0, v138
	v_add_f32_e32 v139, 1.0, v139
	v_mul_f32_e32 v80, v80, v136
	v_mul_f32_e32 v81, v81, v137
	v_mul_f32_e32 v82, v82, v138
	v_mul_f32_e32 v83, v83, v139
	global_load_dwordx4 v[136:139], v129, s[24:25] offset:1024
	s_waitcnt vmcnt(0)
	v_add_f32_e32 v136, 1.0, v136
	v_add_f32_e32 v137, 1.0, v137
	v_add_f32_e32 v138, 1.0, v138
	v_add_f32_e32 v139, 1.0, v139
	v_mul_f32_e32 v84, v84, v136
	v_mul_f32_e32 v85, v85, v137
	v_mul_f32_e32 v86, v86, v138
	v_mul_f32_e32 v87, v87, v139
	global_load_dwordx4 v[136:139], v129, s[24:25] offset:2048
	s_waitcnt vmcnt(0)
	v_add_f32_e32 v136, 1.0, v136
	v_add_f32_e32 v137, 1.0, v137
	v_add_f32_e32 v138, 1.0, v138
	v_add_f32_e32 v139, 1.0, v139
	v_mul_f32_e32 v88, v88, v136
	v_mul_f32_e32 v89, v89, v137
	v_mul_f32_e32 v90, v90, v138
	v_mul_f32_e32 v91, v91, v139
	global_load_dwordx4 v[136:139], v129, s[24:25] offset:3072
	s_waitcnt vmcnt(0)
	v_add_f32_e32 v136, 1.0, v136
	v_add_f32_e32 v137, 1.0, v137
	v_add_f32_e32 v138, 1.0, v138
	v_add_f32_e32 v139, 1.0, v139
	v_mul_f32_e32 v92, v92, v136
	v_mul_f32_e32 v93, v93, v137
	v_mul_f32_e32 v94, v94, v138
	v_mul_f32_e32 v95, v95, v139
.Lp1_np2:
	s_waitcnt vmcnt(16)
	v_mul_f32_e32 v140, v0, v0
	v_mul_f32_e32 v141, v1, v1
	v_fmac_f32_e32 v140, v2, v2
	v_fmac_f32_e32 v141, v3, v3
	v_fmac_f32_e32 v140, v4, v4
	v_fmac_f32_e32 v141, v5, v5
	v_fmac_f32_e32 v140, v6, v6
	v_fmac_f32_e32 v141, v7, v7
	v_fmac_f32_e32 v140, v8, v8
	v_fmac_f32_e32 v141, v9, v9
	v_fmac_f32_e32 v140, v10, v10
	v_fmac_f32_e32 v141, v11, v11
	v_fmac_f32_e32 v140, v12, v12
	v_fmac_f32_e32 v141, v13, v13
	v_fmac_f32_e32 v140, v14, v14
	v_fmac_f32_e32 v141, v15, v15
	v_fmac_f32_e32 v140, v16, v16
	v_fmac_f32_e32 v141, v17, v17
	v_fmac_f32_e32 v140, v18, v18
	v_fmac_f32_e32 v141, v19, v19
	v_fmac_f32_e32 v140, v20, v20
	v_fmac_f32_e32 v141, v21, v21
	v_fmac_f32_e32 v140, v22, v22
	v_fmac_f32_e32 v141, v23, v23
	v_fmac_f32_e32 v140, v24, v24
	v_fmac_f32_e32 v141, v25, v25
	v_fmac_f32_e32 v140, v26, v26
	v_fmac_f32_e32 v141, v27, v27
	v_fmac_f32_e32 v140, v28, v28
	v_fmac_f32_e32 v141, v29, v29
	v_fmac_f32_e32 v140, v30, v30
	v_fmac_f32_e32 v141, v31, v31
	v_add_f32_e32 v140, v140, v141
	s_nop 1
	v_add_f32_dpp v142, v140, v140 quad_perm:[1,0,3,2] row_mask:0xf bank_mask:0xf
	s_nop 1
	v_add_f32_dpp v142, v142, v142 quad_perm:[2,3,0,1] row_mask:0xf bank_mask:0xf
	s_nop 1
	v_add_f32_dpp v142, v142, v142 row_half_mirror row_mask:0xf bank_mask:0xf
	s_nop 1
	v_add_f32_dpp v142, v142, v142 row_mirror row_mask:0xf bank_mask:0xf
	s_nop 1
	v_readlane_b32 s20, v142, 0
	v_readlane_b32 s21, v142, 16
	v_readlane_b32 s22, v142, 32
	v_readlane_b32 s23, v142, 48
	s_nop 1
	v_mov_b32_e32 v143, s20
	v_add_f32_e32 v143, s21, v143
	v_add_f32_e32 v143, s22, v143
	v_add_f32_e32 v143, s23, v143
	v_fmamk_f32 v143, v143, 0x3a000000, v131
	v_rsq_f32_e32 v143, v143
	s_nop 0
	s_add_i32 s4, s6, 2
	s_lshl_b32 s5, s4, 12
	s_add_u32 s14, s84, s5
	s_addc_u32 s15, s85, 0
	s_add_u32 s14, s14, 0x11800000
	s_addc_u32 s15, s15, 0
	v_mul_f32_e32 v136, v143, v0
	v_mul_f32_e32 v137, v143, v1
	v_mul_f32_e32 v138, v143, v2
	v_mul_f32_e32 v139, v143, v3
	v_fma_f32 v136, v136, v64, v96
	v_fma_f32 v137, v137, v65, v97
	v_fma_f32 v138, v138, v66, v98
	v_fma_f32 v139, v139, v67, v99
	v_cvt_pk_bf16_f32 v132, v136, v137
	v_cvt_pk_bf16_f32 v133, v138, v139
	global_store_dwordx2 v130, v[132:133], s[14:15] offset:0
	v_mul_f32_e32 v136, v143, v4
	v_mul_f32_e32 v137, v143, v5
	v_mul_f32_e32 v138, v143, v6
	v_mul_f32_e32 v139, v143, v7
	v_fma_f32 v136, v136, v68, v100
	v_fma_f32 v137, v137, v69, v101
	v_fma_f32 v138, v138, v70, v102
	v_fma_f32 v139, v139, v71, v103
	v_cvt_pk_bf16_f32 v134, v136, v137
	v_cvt_pk_bf16_f32 v135, v138, v139
	global_store_dwordx2 v130, v[134:135], s[14:15] offset:512
	v_mul_f32_e32 v136, v143, v8
	v_mul_f32_e32 v137, v143, v9
	v_mul_f32_e32 v138, v143, v10
	v_mul_f32_e32 v139, v143, v11
	v_fma_f32 v136, v136, v72, v104
	v_fma_f32 v137, v137, v73, v105
	v_fma_f32 v138, v138, v74, v106
	v_fma_f32 v139, v139, v75, v107
	v_cvt_pk_bf16_f32 v132, v136, v137
	v_cvt_pk_bf16_f32 v133, v138, v139
	global_store_dwordx2 v130, v[132:133], s[14:15] offset:1024
	v_mul_f32_e32 v136, v143, v12
	v_mul_f32_e32 v137, v143, v13
	v_mul_f32_e32 v138, v143, v14
	v_mul_f32_e32 v139, v143, v15
	v_fma_f32 v136, v136, v76, v108
	v_fma_f32 v137, v137, v77, v109
	v_fma_f32 v138, v138, v78, v110
	v_fma_f32 v139, v139, v79, v111
	v_cvt_pk_bf16_f32 v134, v136, v137
	v_cvt_pk_bf16_f32 v135, v138, v139
	global_store_dwordx2 v130, v[134:135], s[14:15] offset:1536
	v_mul_f32_e32 v136, v143, v16
	v_mul_f32_e32 v137, v143, v17
; __device__ __forceinline__ unsigned cvt_pk_bf16(float lo, float hi) { unsigned r; asm volatile("v_cvt_pk_bf16_f32 %0, %1, %2" : "=v"(r) : "v"(lo), "v"(hi)); return r; }
; __device__ __forceinline__ void modulate_store(const f32x4 (&v)[8], float rstd, const float* pn, const float* modr, bf16_t* orow, int lane) {
; #pragma unroll
;     for (int j = 0; j < 8; ++j) { const int col = 4 * lane + 256 * j;
;         const f32x4 g = *(const f32x4*)(pn + col), sh = *(const f32x4*)(modr + col), sc = *(const f32x4*)(modr + DM + col);
;         const f32x4 hh = v[j] * rstd * g * (sc + 1.f) + sh;
;         u32x2 w; w.x = cvt_pk_bf16(hh[0], hh[1]); w.y = cvt_pk_bf16(hh[2], hh[3]);
;         *(u32x2*)(orow + col) = w; }
; }
; __global__ void __launch_bounds__(NWAVES * 64, 2) mk_fwd(Args args) {
;     ...
;         for (int row0 = F.gw * 3; row0 < MT; row0 += F.NGW * 3) {
;             f32x4 v[3][8];
; #pragma unroll
;             for (int q = 0; q < 3; ++q) { const int row = row0 + q; const float* src = row < ML ? x + (size_t)row * DM : ctx + (size_t)(row - ML) * DM; load_row_f32(src, F.lane, v[q]); }
; #pragma unroll
;             for (int q = 0; q < 3; ++q) { const int row = row0 + q; const int r = row < ML ? row / SEQ : 8;
;                 const float rstd = __builtin_amdgcn_rsqf(sumsq8(v[q]) * (1.f / DM) + EPS);
;                 modulate_store(v[q], rstd, pre_norm, mod + (size_t)r * 6144, H + (size_t)row * DM, F.lane); }
;         }
	v_mul_f32_e32 v138, v143, v18
	v_mul_f32_e32 v139, v143, v19
	v_fma_f32 v136, v136, v80, v112
	v_fma_f32 v137, v137, v81, v113
	v_fma_f32 v138, v138, v82, v114
	v_fma_f32 v139, v139, v83, v115
	v_cvt_pk_bf16_f32 v132, v136, v137
	v_cvt_pk_bf16_f32 v133, v138, v139
	global_store_dwordx2 v130, v[132:133], s[14:15] offset:2048
	v_mul_f32_e32 v136, v143, v20
	v_mul_f32_e32 v137, v143, v21
	v_mul_f32_e32 v138, v143, v22
	v_mul_f32_e32 v139, v143, v23
	v_fma_f32 v136, v136, v84, v116
	v_fma_f32 v137, v137, v85, v117
	v_fma_f32 v138, v138, v86, v118
	v_fma_f32 v139, v139, v87, v119
	v_cvt_pk_bf16_f32 v134, v136, v137
	v_cvt_pk_bf16_f32 v135, v138, v139
	global_store_dwordx2 v130, v[134:135], s[14:15] offset:2560
	v_mul_f32_e32 v136, v143, v24
	v_mul_f32_e32 v137, v143, v25
	v_mul_f32_e32 v138, v143, v26
	v_mul_f32_e32 v139, v143, v27
	v_fma_f32 v136, v136, v88, v120
	v_fma_f32 v137, v137, v89, v121
	v_fma_f32 v138, v138, v90, v122
	v_fma_f32 v139, v139, v91, v123
	v_cvt_pk_bf16_f32 v132, v136, v137
	v_cvt_pk_bf16_f32 v133, v138, v139
	global_store_dwordx2 v130, v[132:133], s[14:15] offset:3072
	v_mul_f32_e32 v136, v143, v28
	v_mul_f32_e32 v137, v143, v29
	v_mul_f32_e32 v138, v143, v30
	v_mul_f32_e32 v139, v143, v31
	v_fma_f32 v136, v136, v92, v124
	v_fma_f32 v137, v137, v93, v125
	v_fma_f32 v138, v138, v94, v126
	v_fma_f32 v139, v139, v95, v127
	v_cvt_pk_bf16_f32 v134, v136, v137
	v_cvt_pk_bf16_f32 v135, v138, v139
	global_store_dwordx2 v130, v[134:135], s[14:15] offset:3584
	s_add_i32 s4, s6, 4
	s_cmp_lt_u32 s4, 0x4000
	s_cselect_b32 s10, s68, s72
	s_cselect_b32 s11, s69, s73
	s_cselect_b32 s5, 0, 0x4000
	s_sub_i32 s5, s4, s5
	s_lshl_b32 s5, s5, 13
	s_add_u32 s10, s10, s5
	s_addc_u32 s11, s11, 0
	global_load_dwordx4 v[0:3], v128, s[10:11] offset:0 nt
	global_load_dwordx4 v[4:7], v128, s[10:11] offset:1024 nt
	global_load_dwordx4 v[8:11], v128, s[10:11] offset:2048 nt
	global_load_dwordx4 v[12:15], v128, s[10:11] offset:3072 nt
	global_load_dwordx4 v[16:19], v129, s[10:11] offset:0 nt
	global_load_dwordx4 v[20:23], v129, s[10:11] offset:1024 nt
	global_load_dwordx4 v[24:27], v129, s[10:11] offset:2048 nt
	global_load_dwordx4 v[28:31], v129, s[10:11] offset:3072 nt
	s_add_i32 s4, s6, 3
	s_add_i32 s4, s6, 3
	s_lshr_b32 s8, s4, 11
	s_cmp_lt_u32 s4, 0x4000
	s_cselect_b32 s8, s8, 8
	s_cmp_eq_u32 s8, s7
	s_cbranch_scc1 .Lp1_np3
	s_mov_b32 s7, s8
	s_add_i32 s5, s8, 0
	s_mul_i32 s5, s5, 0x6000
	s_add_u32 s24, s84, s5
	s_addc_u32 s25, s85, 0
	s_add_u32 s24, s24, 0x2000
	s_addc_u32 s25, s25, 0
	s_add_i32 s5, s8, 0
	s_mul_i32 s5, s5, 0x6000
	s_add_u32 s16, s84, s5
	s_addc_u32 s17, s85, 0
	s_add_u32 s18, s80, 0x0
	s_addc_u32 s19, s81, 0
	global_load_dwordx4 v[64:67], v128, s[18:19] offset:0
	global_load_dwordx4 v[96:99], v128, s[16:17] offset:0
	global_load_dwordx4 v[68:71], v128, s[18:19] offset:1024
	global_load_dwordx4 v[100:103], v128, s[16:17] offset:1024
	global_load_dwordx4 v[72:75], v128, s[18:19] offset:2048
	global_load_dwordx4 v[104:107], v128, s[16:17] offset:2048
	global_load_dwordx4 v[76:79], v128, s[18:19] offset:3072
	global_load_dwordx4 v[108:111], v128, s[16:17] offset:3072
	global_load_dwordx4 v[80:83], v129, s[18:19] offset:0
	global_load_dwordx4 v[112:115], v129, s[16:17] offset:0
	global_load_dwordx4 v[84:87], v129, s[18:19] offset:1024
	global_load_dwordx4 v[116:119], v129, s[16:17] offset:1024
	global_load_dwordx4 v[88:91], v129, s[18:19] offset:2048
	global_load_dwordx4 v[120:123], v129, s[16:17] offset:2048
	global_load_dwordx4 v[92:95], v129, s[18:19] offset:3072
	global_load_dwordx4 v[124:127], v129, s[16:17] offset:3072
	global_load_dwordx4 v[136:139], v128, s[24:25] offset:0
	s_waitcnt vmcnt(0)
	v_add_f32_e32 v136, 1.0, v136
	v_add_f32_e32 v137, 1.0, v137
	v_add_f32_e32 v138, 1.0, v138
	v_add_f32_e32 v139, 1.0, v139
	v_mul_f32_e32 v64, v64, v136
	v_mul_f32_e32 v65, v65, v137
	v_mul_f32_e32 v66, v66, v138
	v_mul_f32_e32 v67, v67, v139
	global_load_dwordx4 v[136:139], v128, s[24:25] offset:1024
	s_waitcnt vmcnt(0)
	v_add_f32_e32 v136, 1.0, v136
	v_add_f32_e32 v137, 1.0, v137
	v_add_f32_e32 v138, 1.0, v138
	v_add_f32_e32 v139, 1.0, v139
	v_mul_f32_e32 v68, v68, v136
	v_mul_f32_e32 v69, v69, v137
	v_mul_f32_e32 v70, v70, v138
	v_mul_f32_e32 v71, v71, v139
	global_load_dwordx4 v[136:139], v128, s[24:25] offset:2048
	s_waitcnt vmcnt(0)
	v_add_f32_e32 v136, 1.0, v136
	v_add_f32_e32 v137, 1.0, v137
	v_add_f32_e32 v138, 1.0, v138
	v_add_f32_e32 v139, 1.0, v139
	v_mul_f32_e32 v72, v72, v136
	v_mul_f32_e32 v73, v73, v137
	v_mul_f32_e32 v74, v74, v138
	v_mul_f32_e32 v75, v75, v139
	global_load_dwordx4 v[136:139], v128, s[24:25] offset:3072
	s_waitcnt vmcnt(0)
	v_add_f32_e32 v136, 1.0, v136
	v_add_f32_e32 v137, 1.0, v137
	v_add_f32_e32 v138, 1.0, v138
	v_add_f32_e32 v139, 1.0, v139
	v_mul_f32_e32 v76, v76, v136
	v_mul_f32_e32 v77, v77, v137
	v_mul_f32_e32 v78, v78, v138
	v_mul_f32_e32 v79, v79, v139
	global_load_dwordx4 v[136:139], v129, s[24:25] offset:0
	s_waitcnt vmcnt(0)
	v_add_f32_e32 v136, 1.0, v136
	v_add_f32_e32 v137, 1.0, v137
	v_add_f32_e32 v138, 1.0, v138
	v_add_f32_e32 v139, 1.0, v139
	v_mul_f32_e32 v80, v80, v136
	v_mul_f32_e32 v81, v81, v137
	v_mul_f32_e32 v82, v82, v138
	v_mul_f32_e32 v83, v83, v139
	global_load_dwordx4 v[136:139], v129, s[24:25] offset:1024
	s_waitcnt vmcnt(0)
	v_add_f32_e32 v136, 1.0, v136
	v_add_f32_e32 v137, 1.0, v137
	v_add_f32_e32 v138, 1.0, v138
	v_add_f32_e32 v139, 1.0, v139
	v_mul_f32_e32 v84, v84, v136
	v_mul_f32_e32 v85, v85, v137
	v_mul_f32_e32 v86, v86, v138
	v_mul_f32_e32 v87, v87, v139
	global_load_dwordx4 v[136:139], v129, s[24:25] offset:2048
	s_waitcnt vmcnt(0)
	v_add_f32_e32 v136, 1.0, v136
	v_add_f32_e32 v137, 1.0, v137
	v_add_f32_e32 v138, 1.0, v138
	v_add_f32_e32 v139, 1.0, v139
	v_mul_f32_e32 v88, v88, v136
	v_mul_f32_e32 v89, v89, v137
	v_mul_f32_e32 v90, v90, v138
	v_mul_f32_e32 v91, v91, v139
	global_load_dwordx4 v[136:139], v129, s[24:25] offset:3072
	s_waitcnt vmcnt(0)
	v_add_f32_e32 v136, 1.0, v136
	v_add_f32_e32 v137, 1.0, v137
	v_add_f32_e32 v138, 1.0, v138
	v_add_f32_e32 v139, 1.0, v139
	v_mul_f32_e32 v92, v92, v136
	v_mul_f32_e32 v93, v93, v137
	v_mul_f32_e32 v94, v94, v138
	v_mul_f32_e32 v95, v95, v139
; __device__ __forceinline__ unsigned cvt_pk_bf16(float lo, float hi) { unsigned r; asm volatile("v_cvt_pk_bf16_f32 %0, %1, %2" : "=v"(r) : "v"(lo), "v"(hi)); return r; }
; __device__ __forceinline__ void load_row_f32(const float* p, int lane, f32x4 (&v)[8]) {
; #pragma unroll
;     for (int j = 0; j < 8; ++j) v[j] = *(const f32x4*)(p + 4 * lane + 256 * j);
; }
; __device__ __forceinline__ float sumsq8(const f32x4 (&v)[8]) {
;     float s = 0.f;
; #pragma unroll
;     for (int j = 0; j < 8; ++j) s += (v[j][0] * v[j][0] + v[j][1] * v[j][1]) + (v[j][2] * v[j][2] + v[j][3] * v[j][3]);
;     return wave_sum(s);
; }
; __device__ __forceinline__ void modulate_store(const f32x4 (&v)[8], float rstd, const float* pn, const float* modr, bf16_t* orow, int lane) {
; #pragma unroll
;     for (int j = 0; j < 8; ++j) { const int col = 4 * lane + 256 * j;
;         const f32x4 g = *(const f32x4*)(pn + col), sh = *(const f32x4*)(modr + col), sc = *(const f32x4*)(modr + DM + col);
;         const f32x4 hh = v[j] * rstd * g * (sc + 1.f) + sh;
;         u32x2 w; w.x = cvt_pk_bf16(hh[0], hh[1]); w.y = cvt_pk_bf16(hh[2], hh[3]);
;         *(u32x2*)(orow + col) = w; }
; }
; __global__ void __launch_bounds__(NWAVES * 64, 2) mk_fwd(Args args) {
;     ...
;         for (int row0 = F.gw * 3; row0 < MT; row0 += F.NGW * 3) {
;             f32x4 v[3][8];
; #pragma unroll
;             for (int q = 0; q < 3; ++q) { const int row = row0 + q; const float* src = row < ML ? x + (size_t)row * DM : ctx + (size_t)(row - ML) * DM; load_row_f32(src, F.lane, v[q]); }
; #pragma unroll
;             for (int q = 0; q < 3; ++q) { const int row = row0 + q; const int r = row < ML ? row / SEQ : 8;
;                 const float rstd = __builtin_amdgcn_rsqf(sumsq8(v[q]) * (1.f / DM) + EPS);
;                 modulate_store(v[q], rstd, pre_norm, mod + (size_t)r * 6144, H + (size_t)row * DM, F.lane); }
;         }
.Lp1_np3:
	s_waitcnt vmcnt(16)
	v_mul_f32_e32 v140, v32, v32
	v_mul_f32_e32 v141, v33, v33
	v_fmac_f32_e32 v140, v34, v34
	v_fmac_f32_e32 v141, v35, v35
	v_fmac_f32_e32 v140, v36, v36
	v_fmac_f32_e32 v141, v37, v37
	v_fmac_f32_e32 v140, v38, v38
	v_fmac_f32_e32 v141, v39, v39
	v_fmac_f32_e32 v140, v40, v40
	v_fmac_f32_e32 v141, v41, v41
	v_fmac_f32_e32 v140, v42, v42
	v_fmac_f32_e32 v141, v43, v43
	v_fmac_f32_e32 v140, v44, v44
	v_fmac_f32_e32 v141, v45, v45
	v_fmac_f32_e32 v140, v46, v46
	v_fmac_f32_e32 v141, v47, v47
	v_fmac_f32_e32 v140, v48, v48
	v_fmac_f32_e32 v141, v49, v49
	v_fmac_f32_e32 v140, v50, v50
	v_fmac_f32_e32 v141, v51, v51
	v_fmac_f32_e32 v140, v52, v52
	v_fmac_f32_e32 v141, v53, v53
	v_fmac_f32_e32 v140, v54, v54
	v_fmac_f32_e32 v141, v55, v55
	v_fmac_f32_e32 v140, v56, v56
	v_fmac_f32_e32 v141, v57, v57
	v_fmac_f32_e32 v140, v58, v58
	v_fmac_f32_e32 v141, v59, v59
	v_fmac_f32_e32 v140, v60, v60
	v_fmac_f32_e32 v141, v61, v61
	v_fmac_f32_e32 v140, v62, v62
	v_fmac_f32_e32 v141, v63, v63
	v_add_f32_e32 v140, v140, v141
	s_nop 1
	v_add_f32_dpp v142, v140, v140 quad_perm:[1,0,3,2] row_mask:0xf bank_mask:0xf
	s_nop 1
	v_add_f32_dpp v142, v142, v142 quad_perm:[2,3,0,1] row_mask:0xf bank_mask:0xf
	s_nop 1
	v_add_f32_dpp v142, v142, v142 row_half_mirror row_mask:0xf bank_mask:0xf
	s_nop 1
	v_add_f32_dpp v142, v142, v142 row_mirror row_mask:0xf bank_mask:0xf
	s_nop 1
	v_readlane_b32 s20, v142, 0
	v_readlane_b32 s21, v142, 16
	v_readlane_b32 s22, v142, 32
	v_readlane_b32 s23, v142, 48
	s_nop 1
	v_mov_b32_e32 v143, s20
	v_add_f32_e32 v143, s21, v143
	v_add_f32_e32 v143, s22, v143
	v_add_f32_e32 v143, s23, v143
	v_fmamk_f32 v143, v143, 0x3a000000, v131
	v_rsq_f32_e32 v143, v143
	s_nop 0
	s_add_i32 s4, s6, 3
	s_lshl_b32 s5, s4, 12
	s_add_u32 s14, s84, s5
	s_addc_u32 s15, s85, 0
	s_add_u32 s14, s14, 0x11800000
	s_addc_u32 s15, s15, 0
	v_mul_f32_e32 v136, v143, v32
	v_mul_f32_e32 v137, v143, v33
	v_mul_f32_e32 v138, v143, v34
	v_mul_f32_e32 v139, v143, v35
	v_fma_f32 v136, v136, v64, v96
	v_fma_f32 v137, v137, v65, v97
	v_fma_f32 v138, v138, v66, v98
	v_fma_f32 v139, v139, v67, v99
	v_cvt_pk_bf16_f32 v132, v136, v137
	v_cvt_pk_bf16_f32 v133, v138, v139
	global_store_dwordx2 v130, v[132:133], s[14:15] offset:0
	v_mul_f32_e32 v136, v143, v36
	v_mul_f32_e32 v137, v143, v37
	v_mul_f32_e32 v138, v143, v38
	v_mul_f32_e32 v139, v143, v39
	v_fma_f32 v136, v136, v68, v100
	v_fma_f32 v137, v137, v69, v101
	v_fma_f32 v138, v138, v70, v102
	v_fma_f32 v139, v139, v71, v103
	v_cvt_pk_bf16_f32 v134, v136, v137
	v_cvt_pk_bf16_f32 v135, v138, v139
	global_store_dwordx2 v130, v[134:135], s[14:15] offset:512
	v_mul_f32_e32 v136, v143, v40
	v_mul_f32_e32 v137, v143, v41
	v_mul_f32_e32 v138, v143, v42
	v_mul_f32_e32 v139, v143, v43
	v_fma_f32 v136, v136, v72, v104
	v_fma_f32 v137, v137, v73, v105
	v_fma_f32 v138, v138, v74, v106
	v_fma_f32 v139, v139, v75, v107
	v_cvt_pk_bf16_f32 v132, v136, v137
	v_cvt_pk_bf16_f32 v133, v138, v139
	global_store_dwordx2 v130, v[132:133], s[14:15] offset:1024
	v_mul_f32_e32 v136, v143, v44
	v_mul_f32_e32 v137, v143, v45
	v_mul_f32_e32 v138, v143, v46
	v_mul_f32_e32 v139, v143, v47
	v_fma_f32 v136, v136, v76, v108
	v_fma_f32 v137, v137, v77, v109
	v_fma_f32 v138, v138, v78, v110
	v_fma_f32 v139, v139, v79, v111
	v_cvt_pk_bf16_f32 v134, v136, v137
	v_cvt_pk_bf16_f32 v135, v138, v139
	global_store_dwordx2 v130, v[134:135], s[14:15] offset:1536
	v_mul_f32_e32 v136, v143, v48
	v_mul_f32_e32 v137, v143, v49
	v_mul_f32_e32 v138, v143, v50
	v_mul_f32_e32 v139, v143, v51
	v_fma_f32 v136, v136, v80, v112
	v_fma_f32 v137, v137, v81, v113
	v_fma_f32 v138, v138, v82, v114
	v_fma_f32 v139, v139, v83, v115
	v_cvt_pk_bf16_f32 v132, v136, v137
	v_cvt_pk_bf16_f32 v133, v138, v139
	global_store_dwordx2 v130, v[132:133], s[14:15] offset:2048
	v_mul_f32_e32 v136, v143, v52
	v_mul_f32_e32 v137, v143, v53
	v_mul_f32_e32 v138, v143, v54
	v_mul_f32_e32 v139, v143, v55
	v_fma_f32 v136, v136, v84, v116
	v_fma_f32 v137, v137, v85, v117
	v_fma_f32 v138, v138, v86, v118
	v_fma_f32 v139, v139, v87, v119
	v_cvt_pk_bf16_f32 v134, v136, v137
	v_cvt_pk_bf16_f32 v135, v138, v139
	global_store_dwordx2 v130, v[134:135], s[14:15] offset:2560
	v_mul_f32_e32 v136, v143, v56
	v_mul_f32_e32 v137, v143, v57
	v_mul_f32_e32 v138, v143, v58
	v_mul_f32_e32 v139, v143, v59
	v_fma_f32 v136, v136, v88, v120
	v_fma_f32 v137, v137, v89, v121
	v_fma_f32 v138, v138, v90, v122
	v_fma_f32 v139, v139, v91, v123
	v_cvt_pk_bf16_f32 v132, v136, v137
	v_cvt_pk_bf16_f32 v133, v138, v139
	global_store_dwordx2 v130, v[132:133], s[14:15] offset:3072
	v_mul_f32_e32 v136, v143, v60
	v_mul_f32_e32 v137, v143, v61
	v_mul_f32_e32 v138, v143, v62
	v_mul_f32_e32 v139, v143, v63
	v_fma_f32 v136, v136, v92, v124
	v_fma_f32 v137, v137, v93, v125
	v_fma_f32 v138, v138, v94, v126
	v_fma_f32 v139, v139, v95, v127
	v_cvt_pk_bf16_f32 v134, v136, v137
	v_cvt_pk_bf16_f32 v135, v138, v139
	global_store_dwordx2 v130, v[134:135], s[14:15] offset:3584
	s_add_i32 s4, s6, 5
	s_cmp_lt_u32 s4, 0x4000
	s_cselect_b32 s10, s68, s72
	s_cselect_b32 s11, s69, s73
	s_cselect_b32 s5, 0, 0x4000
	s_sub_i32 s5, s4, s5
	s_lshl_b32 s5, s5, 13
	s_add_u32 s10, s10, s5
	s_addc_u32 s11, s11, 0
	global_load_dwordx4 v[32:35], v128, s[10:11] offset:0 nt
	global_load_dwordx4 v[36:39], v128, s[10:11] offset:1024 nt
	global_load_dwordx4 v[40:43], v128, s[10:11] offset:2048 nt
	global_load_dwordx4 v[44:47], v128, s[10:11] offset:3072 nt
	global_load_dwordx4 v[48:51], v129, s[10:11] offset:0 nt
	global_load_dwordx4 v[52:55], v129, s[10:11] offset:1024 nt
	global_load_dwordx4 v[56:59], v129, s[10:11] offset:2048 nt
	global_load_dwordx4 v[60:63], v129, s[10:11] offset:3072 nt
	s_add_i32 s4, s6, 4
	s_add_i32 s4, s6, 4
	s_lshr_b32 s8, s4, 11
	s_cmp_lt_u32 s4, 0x4000
	s_cselect_b32 s8, s8, 8
	s_cmp_eq_u32 s8, s7
	s_cbranch_scc1 .Lp1_np4
; __device__ __forceinline__ unsigned cvt_pk_bf16(float lo, float hi) { unsigned r; asm volatile("v_cvt_pk_bf16_f32 %0, %1, %2" : "=v"(r) : "v"(lo), "v"(hi)); return r; }
; __device__ __forceinline__ void modulate_store(const f32x4 (&v)[8], float rstd, const float* pn, const float* modr, bf16_t* orow, int lane) {
; #pragma unroll
;     for (int j = 0; j < 8; ++j) { const int col = 4 * lane + 256 * j;
;         const f32x4 g = *(const f32x4*)(pn + col), sh = *(const f32x4*)(modr + col), sc = *(const f32x4*)(modr + DM + col);
;         const f32x4 hh = v[j] * rstd * g * (sc + 1.f) + sh;
;         u32x2 w; w.x = cvt_pk_bf16(hh[0], hh[1]); w.y = cvt_pk_bf16(hh[2], hh[3]);
;         *(u32x2*)(orow + col) = w; }
; }
; __global__ void __launch_bounds__(NWAVES * 64, 2) mk_fwd(Args args) {
;     ...
;         for (int row0 = F.gw * 3; row0 < MT; row0 += F.NGW * 3) {
;             f32x4 v[3][8];
; #pragma unroll
;             for (int q = 0; q < 3; ++q) { const int row = row0 + q; const float* src = row < ML ? x + (size_t)row * DM : ctx + (size_t)(row - ML) * DM; load_row_f32(src, F.lane, v[q]); }
; #pragma unroll
;             for (int q = 0; q < 3; ++q) { const int row = row0 + q; const int r = row < ML ? row / SEQ : 8;
;                 const float rstd = __builtin_amdgcn_rsqf(sumsq8(v[q]) * (1.f / DM) + EPS);
;                 modulate_store(v[q], rstd, pre_norm, mod + (size_t)r * 6144, H + (size_t)row * DM, F.lane); }
;         }
	s_mov_b32 s7, s8
	s_add_i32 s5, s8, 0
	s_mul_i32 s5, s5, 0x6000
	s_add_u32 s24, s84, s5
	s_addc_u32 s25, s85, 0
	s_add_u32 s24, s24, 0x2000
	s_addc_u32 s25, s25, 0
	s_add_i32 s5, s8, 0
	s_mul_i32 s5, s5, 0x6000
	s_add_u32 s16, s84, s5
	s_addc_u32 s17, s85, 0
	s_add_u32 s18, s80, 0x0
	s_addc_u32 s19, s81, 0
	global_load_dwordx4 v[64:67], v128, s[18:19] offset:0
	global_load_dwordx4 v[96:99], v128, s[16:17] offset:0
	global_load_dwordx4 v[68:71], v128, s[18:19] offset:1024
	global_load_dwordx4 v[100:103], v128, s[16:17] offset:1024
	global_load_dwordx4 v[72:75], v128, s[18:19] offset:2048
	global_load_dwordx4 v[104:107], v128, s[16:17] offset:2048
	global_load_dwordx4 v[76:79], v128, s[18:19] offset:3072
	global_load_dwordx4 v[108:111], v128, s[16:17] offset:3072
	global_load_dwordx4 v[80:83], v129, s[18:19] offset:0
	global_load_dwordx4 v[112:115], v129, s[16:17] offset:0
	global_load_dwordx4 v[84:87], v129, s[18:19] offset:1024
	global_load_dwordx4 v[116:119], v129, s[16:17] offset:1024
	global_load_dwordx4 v[88:91], v129, s[18:19] offset:2048
	global_load_dwordx4 v[120:123], v129, s[16:17] offset:2048
	global_load_dwordx4 v[92:95], v129, s[18:19] offset:3072
	global_load_dwordx4 v[124:127], v129, s[16:17] offset:3072
	global_load_dwordx4 v[136:139], v128, s[24:25] offset:0
	s_waitcnt vmcnt(0)
	v_add_f32_e32 v136, 1.0, v136
	v_add_f32_e32 v137, 1.0, v137
	v_add_f32_e32 v138, 1.0, v138
	v_add_f32_e32 v139, 1.0, v139
	v_mul_f32_e32 v64, v64, v136
	v_mul_f32_e32 v65, v65, v137
	v_mul_f32_e32 v66, v66, v138
	v_mul_f32_e32 v67, v67, v139
	global_load_dwordx4 v[136:139], v128, s[24:25] offset:1024
	s_waitcnt vmcnt(0)
	v_add_f32_e32 v136, 1.0, v136
	v_add_f32_e32 v137, 1.0, v137
	v_add_f32_e32 v138, 1.0, v138
	v_add_f32_e32 v139, 1.0, v139
	v_mul_f32_e32 v68, v68, v136
	v_mul_f32_e32 v69, v69, v137
	v_mul_f32_e32 v70, v70, v138
	v_mul_f32_e32 v71, v71, v139
	global_load_dwordx4 v[136:139], v128, s[24:25] offset:2048
	s_waitcnt vmcnt(0)
	v_add_f32_e32 v136, 1.0, v136
	v_add_f32_e32 v137, 1.0, v137
	v_add_f32_e32 v138, 1.0, v138
	v_add_f32_e32 v139, 1.0, v139
	v_mul_f32_e32 v72, v72, v136
	v_mul_f32_e32 v73, v73, v137
	v_mul_f32_e32 v74, v74, v138
	v_mul_f32_e32 v75, v75, v139
	global_load_dwordx4 v[136:139], v128, s[24:25] offset:3072
	s_waitcnt vmcnt(0)
	v_add_f32_e32 v136, 1.0, v136
	v_add_f32_e32 v137, 1.0, v137
	v_add_f32_e32 v138, 1.0, v138
	v_add_f32_e32 v139, 1.0, v139
	v_mul_f32_e32 v76, v76, v136
	v_mul_f32_e32 v77, v77, v137
	v_mul_f32_e32 v78, v78, v138
	v_mul_f32_e32 v79, v79, v139
	global_load_dwordx4 v[136:139], v129, s[24:25] offset:0
	s_waitcnt vmcnt(0)
	v_add_f32_e32 v136, 1.0, v136
	v_add_f32_e32 v137, 1.0, v137
	v_add_f32_e32 v138, 1.0, v138
	v_add_f32_e32 v139, 1.0, v139
	v_mul_f32_e32 v80, v80, v136
	v_mul_f32_e32 v81, v81, v137
	v_mul_f32_e32 v82, v82, v138
	v_mul_f32_e32 v83, v83, v139
	global_load_dwordx4 v[136:139], v129, s[24:25] offset:1024
	s_waitcnt vmcnt(0)
	v_add_f32_e32 v136, 1.0, v136
	v_add_f32_e32 v137, 1.0, v137
	v_add_f32_e32 v138, 1.0, v138
	v_add_f32_e32 v139, 1.0, v139
	v_mul_f32_e32 v84, v84, v136
	v_mul_f32_e32 v85, v85, v137
	v_mul_f32_e32 v86, v86, v138
	v_mul_f32_e32 v87, v87, v139
	global_load_dwordx4 v[136:139], v129, s[24:25] offset:2048
	s_waitcnt vmcnt(0)
	v_add_f32_e32 v136, 1.0, v136
	v_add_f32_e32 v137, 1.0, v137
	v_add_f32_e32 v138, 1.0, v138
	v_add_f32_e32 v139, 1.0, v139
	v_mul_f32_e32 v88, v88, v136
	v_mul_f32_e32 v89, v89, v137
	v_mul_f32_e32 v90, v90, v138
	v_mul_f32_e32 v91, v91, v139
	global_load_dwordx4 v[136:139], v129, s[24:25] offset:3072
	s_waitcnt vmcnt(0)
	v_add_f32_e32 v136, 1.0, v136
	v_add_f32_e32 v137, 1.0, v137
	v_add_f32_e32 v138, 1.0, v138
	v_add_f32_e32 v139, 1.0, v139
	v_mul_f32_e32 v92, v92, v136
	v_mul_f32_e32 v93, v93, v137
	v_mul_f32_e32 v94, v94, v138
	v_mul_f32_e32 v95, v95, v139
.Lp1_np4:
	s_waitcnt vmcnt(16)
	v_mul_f32_e32 v140, v0, v0
	v_mul_f32_e32 v141, v1, v1
	v_fmac_f32_e32 v140, v2, v2
	v_fmac_f32_e32 v141, v3, v3
	v_fmac_f32_e32 v140, v4, v4
	v_fmac_f32_e32 v141, v5, v5
	v_fmac_f32_e32 v140, v6, v6
	v_fmac_f32_e32 v141, v7, v7
	v_fmac_f32_e32 v140, v8, v8
	v_fmac_f32_e32 v141, v9, v9
	v_fmac_f32_e32 v140, v10, v10
	v_fmac_f32_e32 v141, v11, v11
	v_fmac_f32_e32 v140, v12, v12
	v_fmac_f32_e32 v141, v13, v13
	v_fmac_f32_e32 v140, v14, v14
	v_fmac_f32_e32 v141, v15, v15
	v_fmac_f32_e32 v140, v16, v16
	v_fmac_f32_e32 v141, v17, v17
	v_fmac_f32_e32 v140, v18, v18
	v_fmac_f32_e32 v141, v19, v19
	v_fmac_f32_e32 v140, v20, v20
	v_fmac_f32_e32 v141, v21, v21
	v_fmac_f32_e32 v140, v22, v22
	v_fmac_f32_e32 v141, v23, v23
	v_fmac_f32_e32 v140, v24, v24
	v_fmac_f32_e32 v141, v25, v25
	v_fmac_f32_e32 v140, v26, v26
	v_fmac_f32_e32 v141, v27, v27
	v_fmac_f32_e32 v140, v28, v28
	v_fmac_f32_e32 v141, v29, v29
	v_fmac_f32_e32 v140, v30, v30
	v_fmac_f32_e32 v141, v31, v31
	v_add_f32_e32 v140, v140, v141
	s_nop 1
	v_add_f32_dpp v142, v140, v140 quad_perm:[1,0,3,2] row_mask:0xf bank_mask:0xf
	s_nop 1
	v_add_f32_dpp v142, v142, v142 quad_perm:[2,3,0,1] row_mask:0xf bank_mask:0xf
	s_nop 1
	v_add_f32_dpp v142, v142, v142 row_half_mirror row_mask:0xf bank_mask:0xf
	s_nop 1
	v_add_f32_dpp v142, v142, v142 row_mirror row_mask:0xf bank_mask:0xf
	s_nop 1
	v_readlane_b32 s20, v142, 0
	v_readlane_b32 s21, v142, 16
	v_readlane_b32 s22, v142, 32
	v_readlane_b32 s23, v142, 48
	s_nop 1
	v_mov_b32_e32 v143, s20
	v_add_f32_e32 v143, s21, v143
	v_add_f32_e32 v143, s22, v143
	v_add_f32_e32 v143, s23, v143
	v_fmamk_f32 v143, v143, 0x3a000000, v131
	v_rsq_f32_e32 v143, v143
	s_nop 0
	s_add_i32 s4, s6, 4
	s_lshl_b32 s5, s4, 12
	s_add_u32 s14, s84, s5
	s_addc_u32 s15, s85, 0
	s_add_u32 s14, s14, 0x11800000
; __device__ __forceinline__ unsigned cvt_pk_bf16(float lo, float hi) { unsigned r; asm volatile("v_cvt_pk_bf16_f32 %0, %1, %2" : "=v"(r) : "v"(lo), "v"(hi)); return r; }
; __device__ __forceinline__ void modulate_store(const f32x4 (&v)[8], float rstd, const float* pn, const float* modr, bf16_t* orow, int lane) {
; #pragma unroll
;     for (int j = 0; j < 8; ++j) { const int col = 4 * lane + 256 * j;
;         const f32x4 g = *(const f32x4*)(pn + col), sh = *(const f32x4*)(modr + col), sc = *(const f32x4*)(modr + DM + col);
;         const f32x4 hh = v[j] * rstd * g * (sc + 1.f) + sh;
;         u32x2 w; w.x = cvt_pk_bf16(hh[0], hh[1]); w.y = cvt_pk_bf16(hh[2], hh[3]);
;         *(u32x2*)(orow + col) = w; }
; }
; __global__ void __launch_bounds__(NWAVES * 64, 2) mk_fwd(Args args) {
;     ...
;         for (int row0 = F.gw * 3; row0 < MT; row0 += F.NGW * 3) {
;             f32x4 v[3][8];
; #pragma unroll
;             for (int q = 0; q < 3; ++q) { const int row = row0 + q; const float* src = row < ML ? x + (size_t)row * DM : ctx + (size_t)(row - ML) * DM; load_row_f32(src, F.lane, v[q]); }
; #pragma unroll
;             for (int q = 0; q < 3; ++q) { const int row = row0 + q; const int r = row < ML ? row / SEQ : 8;
;                 const float rstd = __builtin_amdgcn_rsqf(sumsq8(v[q]) * (1.f / DM) + EPS);
;                 modulate_store(v[q], rstd, pre_norm, mod + (size_t)r * 6144, H + (size_t)row * DM, F.lane); }
;         }
	s_addc_u32 s15, s15, 0
	v_mul_f32_e32 v136, v143, v0
	v_mul_f32_e32 v137, v143, v1
	v_mul_f32_e32 v138, v143, v2
	v_mul_f32_e32 v139, v143, v3
	v_fma_f32 v136, v136, v64, v96
	v_fma_f32 v137, v137, v65, v97
	v_fma_f32 v138, v138, v66, v98
	v_fma_f32 v139, v139, v67, v99
	v_cvt_pk_bf16_f32 v132, v136, v137
	v_cvt_pk_bf16_f32 v133, v138, v139
	global_store_dwordx2 v130, v[132:133], s[14:15] offset:0
	v_mul_f32_e32 v136, v143, v4
	v_mul_f32_e32 v137, v143, v5
	v_mul_f32_e32 v138, v143, v6
	v_mul_f32_e32 v139, v143, v7
	v_fma_f32 v136, v136, v68, v100
	v_fma_f32 v137, v137, v69, v101
	v_fma_f32 v138, v138, v70, v102
	v_fma_f32 v139, v139, v71, v103
	v_cvt_pk_bf16_f32 v134, v136, v137
	v_cvt_pk_bf16_f32 v135, v138, v139
	global_store_dwordx2 v130, v[134:135], s[14:15] offset:512
	v_mul_f32_e32 v136, v143, v8
	v_mul_f32_e32 v137, v143, v9
	v_mul_f32_e32 v138, v143, v10
	v_mul_f32_e32 v139, v143, v11
	v_fma_f32 v136, v136, v72, v104
	v_fma_f32 v137, v137, v73, v105
	v_fma_f32 v138, v138, v74, v106
	v_fma_f32 v139, v139, v75, v107
	v_cvt_pk_bf16_f32 v132, v136, v137
	v_cvt_pk_bf16_f32 v133, v138, v139
	global_store_dwordx2 v130, v[132:133], s[14:15] offset:1024
	v_mul_f32_e32 v136, v143, v12
	v_mul_f32_e32 v137, v143, v13
	v_mul_f32_e32 v138, v143, v14
	v_mul_f32_e32 v139, v143, v15
	v_fma_f32 v136, v136, v76, v108
	v_fma_f32 v137, v137, v77, v109
	v_fma_f32 v138, v138, v78, v110
	v_fma_f32 v139, v139, v79, v111
	v_cvt_pk_bf16_f32 v134, v136, v137
	v_cvt_pk_bf16_f32 v135, v138, v139
	global_store_dwordx2 v130, v[134:135], s[14:15] offset:1536
	v_mul_f32_e32 v136, v143, v16
	v_mul_f32_e32 v137, v143, v17
	v_mul_f32_e32 v138, v143, v18
	v_mul_f32_e32 v139, v143, v19
	v_fma_f32 v136, v136, v80, v112
	v_fma_f32 v137, v137, v81, v113
	v_fma_f32 v138, v138, v82, v114
	v_fma_f32 v139, v139, v83, v115
	v_cvt_pk_bf16_f32 v132, v136, v137
	v_cvt_pk_bf16_f32 v133, v138, v139
	global_store_dwordx2 v130, v[132:133], s[14:15] offset:2048
	v_mul_f32_e32 v136, v143, v20
	v_mul_f32_e32 v137, v143, v21
	v_mul_f32_e32 v138, v143, v22
	v_mul_f32_e32 v139, v143, v23
	v_fma_f32 v136, v136, v84, v116
	v_fma_f32 v137, v137, v85, v117
	v_fma_f32 v138, v138, v86, v118
	v_fma_f32 v139, v139, v87, v119
	v_cvt_pk_bf16_f32 v134, v136, v137
	v_cvt_pk_bf16_f32 v135, v138, v139
	global_store_dwordx2 v130, v[134:135], s[14:15] offset:2560
	v_mul_f32_e32 v136, v143, v24
	v_mul_f32_e32 v137, v143, v25
	v_mul_f32_e32 v138, v143, v26
	v_mul_f32_e32 v139, v143, v27
	v_fma_f32 v136, v136, v88, v120
	v_fma_f32 v137, v137, v89, v121
	v_fma_f32 v138, v138, v90, v122
	v_fma_f32 v139, v139, v91, v123
	v_cvt_pk_bf16_f32 v132, v136, v137
	v_cvt_pk_bf16_f32 v133, v138, v139
	global_store_dwordx2 v130, v[132:133], s[14:15] offset:3072
	v_mul_f32_e32 v136, v143, v28
	v_mul_f32_e32 v137, v143, v29
	v_mul_f32_e32 v138, v143, v30
	v_mul_f32_e32 v139, v143, v31
	v_fma_f32 v136, v136, v92, v124
	v_fma_f32 v137, v137, v93, v125
	v_fma_f32 v138, v138, v94, v126
	v_fma_f32 v139, v139, v95, v127
	v_cvt_pk_bf16_f32 v134, v136, v137
	v_cvt_pk_bf16_f32 v135, v138, v139
	global_store_dwordx2 v130, v[134:135], s[14:15] offset:3584
	s_add_i32 s4, s6, 6
	s_cmp_lt_u32 s4, 0x4000
	s_cselect_b32 s10, s68, s72
	s_cselect_b32 s11, s69, s73
	s_cselect_b32 s5, 0, 0x4000
	s_sub_i32 s5, s4, s5
	s_lshl_b32 s5, s5, 13
	s_add_u32 s10, s10, s5
	s_addc_u32 s11, s11, 0
	global_load_dwordx4 v[0:3], v128, s[10:11] offset:0 nt
	global_load_dwordx4 v[4:7], v128, s[10:11] offset:1024 nt
	global_load_dwordx4 v[8:11], v128, s[10:11] offset:2048 nt
	global_load_dwordx4 v[12:15], v128, s[10:11] offset:3072 nt
	global_load_dwordx4 v[16:19], v129, s[10:11] offset:0 nt
	global_load_dwordx4 v[20:23], v129, s[10:11] offset:1024 nt
	global_load_dwordx4 v[24:27], v129, s[10:11] offset:2048 nt
	global_load_dwordx4 v[28:31], v129, s[10:11] offset:3072 nt
	s_add_i32 s4, s6, 5
	s_add_i32 s4, s6, 5
	s_lshr_b32 s8, s4, 11
	s_cmp_lt_u32 s4, 0x4000
	s_cselect_b32 s8, s8, 8
	s_cmp_eq_u32 s8, s7
	s_cbranch_scc1 .Lp1_np5
	s_mov_b32 s7, s8
	s_add_i32 s5, s8, 0
	s_mul_i32 s5, s5, 0x6000
	s_add_u32 s24, s84, s5
	s_addc_u32 s25, s85, 0
	s_add_u32 s24, s24, 0x2000
	s_addc_u32 s25, s25, 0
	s_add_i32 s5, s8, 0
	s_mul_i32 s5, s5, 0x6000
	s_add_u32 s16, s84, s5
	s_addc_u32 s17, s85, 0
	s_add_u32 s18, s80, 0x0
	s_addc_u32 s19, s81, 0
	global_load_dwordx4 v[64:67], v128, s[18:19] offset:0
	global_load_dwordx4 v[96:99], v128, s[16:17] offset:0
	global_load_dwordx4 v[68:71], v128, s[18:19] offset:1024
	global_load_dwordx4 v[100:103], v128, s[16:17] offset:1024
	global_load_dwordx4 v[72:75], v128, s[18:19] offset:2048
	global_load_dwordx4 v[104:107], v128, s[16:17] offset:2048
	global_load_dwordx4 v[76:79], v128, s[18:19] offset:3072
	global_load_dwordx4 v[108:111], v128, s[16:17] offset:3072
	global_load_dwordx4 v[80:83], v129, s[18:19] offset:0
	global_load_dwordx4 v[112:115], v129, s[16:17] offset:0
	global_load_dwordx4 v[84:87], v129, s[18:19] offset:1024
	global_load_dwordx4 v[116:119], v129, s[16:17] offset:1024
	global_load_dwordx4 v[88:91], v129, s[18:19] offset:2048
	global_load_dwordx4 v[120:123], v129, s[16:17] offset:2048
	global_load_dwordx4 v[92:95], v129, s[18:19] offset:3072
	global_load_dwordx4 v[124:127], v129, s[16:17] offset:3072
	global_load_dwordx4 v[136:139], v128, s[24:25] offset:0
	s_waitcnt vmcnt(0)
	v_add_f32_e32 v136, 1.0, v136
	v_add_f32_e32 v137, 1.0, v137
	v_add_f32_e32 v138, 1.0, v138
	v_add_f32_e32 v139, 1.0, v139
	v_mul_f32_e32 v64, v64, v136
	v_mul_f32_e32 v65, v65, v137
	v_mul_f32_e32 v66, v66, v138
	v_mul_f32_e32 v67, v67, v139
	global_load_dwordx4 v[136:139], v128, s[24:25] offset:1024
	s_waitcnt vmcnt(0)
; __device__ __forceinline__ unsigned cvt_pk_bf16(float lo, float hi) { unsigned r; asm volatile("v_cvt_pk_bf16_f32 %0, %1, %2" : "=v"(r) : "v"(lo), "v"(hi)); return r; }
; __device__ __forceinline__ void modulate_store(const f32x4 (&v)[8], float rstd, const float* pn, const float* modr, bf16_t* orow, int lane) {
; #pragma unroll
;     for (int j = 0; j < 8; ++j) { const int col = 4 * lane + 256 * j;
;         const f32x4 g = *(const f32x4*)(pn + col), sh = *(const f32x4*)(modr + col), sc = *(const f32x4*)(modr + DM + col);
;         const f32x4 hh = v[j] * rstd * g * (sc + 1.f) + sh;
;         u32x2 w; w.x = cvt_pk_bf16(hh[0], hh[1]); w.y = cvt_pk_bf16(hh[2], hh[3]);
;         *(u32x2*)(orow + col) = w; }
; }
; __global__ void __launch_bounds__(NWAVES * 64, 2) mk_fwd(Args args) {
;     ...
;         for (int row0 = F.gw * 3; row0 < MT; row0 += F.NGW * 3) {
;             f32x4 v[3][8];
; #pragma unroll
;             for (int q = 0; q < 3; ++q) { const int row = row0 + q; const float* src = row < ML ? x + (size_t)row * DM : ctx + (size_t)(row - ML) * DM; load_row_f32(src, F.lane, v[q]); }
; #pragma unroll
;             for (int q = 0; q < 3; ++q) { const int row = row0 + q; const int r = row < ML ? row / SEQ : 8;
;                 const float rstd = __builtin_amdgcn_rsqf(sumsq8(v[q]) * (1.f / DM) + EPS);
;                 modulate_store(v[q], rstd, pre_norm, mod + (size_t)r * 6144, H + (size_t)row * DM, F.lane); }
;         }
	v_add_f32_e32 v136, 1.0, v136
	v_add_f32_e32 v137, 1.0, v137
	v_add_f32_e32 v138, 1.0, v138
	v_add_f32_e32 v139, 1.0, v139
	v_mul_f32_e32 v68, v68, v136
	v_mul_f32_e32 v69, v69, v137
	v_mul_f32_e32 v70, v70, v138
	v_mul_f32_e32 v71, v71, v139
	global_load_dwordx4 v[136:139], v128, s[24:25] offset:2048
	s_waitcnt vmcnt(0)
	v_add_f32_e32 v136, 1.0, v136
	v_add_f32_e32 v137, 1.0, v137
	v_add_f32_e32 v138, 1.0, v138
	v_add_f32_e32 v139, 1.0, v139
	v_mul_f32_e32 v72, v72, v136
	v_mul_f32_e32 v73, v73, v137
	v_mul_f32_e32 v74, v74, v138
	v_mul_f32_e32 v75, v75, v139
	global_load_dwordx4 v[136:139], v128, s[24:25] offset:3072
	s_waitcnt vmcnt(0)
	v_add_f32_e32 v136, 1.0, v136
	v_add_f32_e32 v137, 1.0, v137
	v_add_f32_e32 v138, 1.0, v138
	v_add_f32_e32 v139, 1.0, v139
	v_mul_f32_e32 v76, v76, v136
	v_mul_f32_e32 v77, v77, v137
	v_mul_f32_e32 v78, v78, v138
	v_mul_f32_e32 v79, v79, v139
	global_load_dwordx4 v[136:139], v129, s[24:25] offset:0
	s_waitcnt vmcnt(0)
	v_add_f32_e32 v136, 1.0, v136
	v_add_f32_e32 v137, 1.0, v137
	v_add_f32_e32 v138, 1.0, v138
	v_add_f32_e32 v139, 1.0, v139
	v_mul_f32_e32 v80, v80, v136
	v_mul_f32_e32 v81, v81, v137
	v_mul_f32_e32 v82, v82, v138
	v_mul_f32_e32 v83, v83, v139
	global_load_dwordx4 v[136:139], v129, s[24:25] offset:1024
	s_waitcnt vmcnt(0)
	v_add_f32_e32 v136, 1.0, v136
	v_add_f32_e32 v137, 1.0, v137
	v_add_f32_e32 v138, 1.0, v138
	v_add_f32_e32 v139, 1.0, v139
	v_mul_f32_e32 v84, v84, v136
	v_mul_f32_e32 v85, v85, v137
	v_mul_f32_e32 v86, v86, v138
	v_mul_f32_e32 v87, v87, v139
	global_load_dwordx4 v[136:139], v129, s[24:25] offset:2048
	s_waitcnt vmcnt(0)
	v_add_f32_e32 v136, 1.0, v136
	v_add_f32_e32 v137, 1.0, v137
	v_add_f32_e32 v138, 1.0, v138
	v_add_f32_e32 v139, 1.0, v139
	v_mul_f32_e32 v88, v88, v136
	v_mul_f32_e32 v89, v89, v137
	v_mul_f32_e32 v90, v90, v138
	v_mul_f32_e32 v91, v91, v139
	global_load_dwordx4 v[136:139], v129, s[24:25] offset:3072
	s_waitcnt vmcnt(0)
	v_add_f32_e32 v136, 1.0, v136
	v_add_f32_e32 v137, 1.0, v137
	v_add_f32_e32 v138, 1.0, v138
	v_add_f32_e32 v139, 1.0, v139
	v_mul_f32_e32 v92, v92, v136
	v_mul_f32_e32 v93, v93, v137
	v_mul_f32_e32 v94, v94, v138
	v_mul_f32_e32 v95, v95, v139
.Lp1_np5:
	s_waitcnt vmcnt(16)
	v_mul_f32_e32 v140, v32, v32
	v_mul_f32_e32 v141, v33, v33
	v_fmac_f32_e32 v140, v34, v34
	v_fmac_f32_e32 v141, v35, v35
	v_fmac_f32_e32 v140, v36, v36
	v_fmac_f32_e32 v141, v37, v37
	v_fmac_f32_e32 v140, v38, v38
	v_fmac_f32_e32 v141, v39, v39
	v_fmac_f32_e32 v140, v40, v40
	v_fmac_f32_e32 v141, v41, v41
	v_fmac_f32_e32 v140, v42, v42
	v_fmac_f32_e32 v141, v43, v43
	v_fmac_f32_e32 v140, v44, v44
	v_fmac_f32_e32 v141, v45, v45
	v_fmac_f32_e32 v140, v46, v46
	v_fmac_f32_e32 v141, v47, v47
	v_fmac_f32_e32 v140, v48, v48
	v_fmac_f32_e32 v141, v49, v49
	v_fmac_f32_e32 v140, v50, v50
	v_fmac_f32_e32 v141, v51, v51
	v_fmac_f32_e32 v140, v52, v52
	v_fmac_f32_e32 v141, v53, v53
	v_fmac_f32_e32 v140, v54, v54
	v_fmac_f32_e32 v141, v55, v55
	v_fmac_f32_e32 v140, v56, v56
	v_fmac_f32_e32 v141, v57, v57
	v_fmac_f32_e32 v140, v58, v58
	v_fmac_f32_e32 v141, v59, v59
	v_fmac_f32_e32 v140, v60, v60
	v_fmac_f32_e32 v141, v61, v61
	v_fmac_f32_e32 v140, v62, v62
	v_fmac_f32_e32 v141, v63, v63
	v_add_f32_e32 v140, v140, v141
	s_nop 1
	v_add_f32_dpp v142, v140, v140 quad_perm:[1,0,3,2] row_mask:0xf bank_mask:0xf
	s_nop 1
	v_add_f32_dpp v142, v142, v142 quad_perm:[2,3,0,1] row_mask:0xf bank_mask:0xf
	s_nop 1
	v_add_f32_dpp v142, v142, v142 row_half_mirror row_mask:0xf bank_mask:0xf
	s_nop 1
	v_add_f32_dpp v142, v142, v142 row_mirror row_mask:0xf bank_mask:0xf
	s_nop 1
	v_readlane_b32 s20, v142, 0
	v_readlane_b32 s21, v142, 16
	v_readlane_b32 s22, v142, 32
	v_readlane_b32 s23, v142, 48
	s_nop 1
	v_mov_b32_e32 v143, s20
	v_add_f32_e32 v143, s21, v143
	v_add_f32_e32 v143, s22, v143
	v_add_f32_e32 v143, s23, v143
	v_fmamk_f32 v143, v143, 0x3a000000, v131
	v_rsq_f32_e32 v143, v143
	s_nop 0
	s_add_i32 s4, s6, 5
	s_lshl_b32 s5, s4, 12
	s_add_u32 s14, s84, s5
	s_addc_u32 s15, s85, 0
	s_add_u32 s14, s14, 0x11800000
	s_addc_u32 s15, s15, 0
	v_mul_f32_e32 v136, v143, v32
	v_mul_f32_e32 v137, v143, v33
	v_mul_f32_e32 v138, v143, v34
	v_mul_f32_e32 v139, v143, v35
	v_fma_f32 v136, v136, v64, v96
	v_fma_f32 v137, v137, v65, v97
	v_fma_f32 v138, v138, v66, v98
	v_fma_f32 v139, v139, v67, v99
	v_cvt_pk_bf16_f32 v132, v136, v137
	v_cvt_pk_bf16_f32 v133, v138, v139
	global_store_dwordx2 v130, v[132:133], s[14:15] offset:0
	v_mul_f32_e32 v136, v143, v36
	v_mul_f32_e32 v137, v143, v37
	v_mul_f32_e32 v138, v143, v38
	v_mul_f32_e32 v139, v143, v39
	v_fma_f32 v136, v136, v68, v100
	v_fma_f32 v137, v137, v69, v101
	v_fma_f32 v138, v138, v70, v102
	v_fma_f32 v139, v139, v71, v103
	v_cvt_pk_bf16_f32 v134, v136, v137
	v_cvt_pk_bf16_f32 v135, v138, v139
	global_store_dwordx2 v130, v[134:135], s[14:15] offset:512
	v_mul_f32_e32 v136, v143, v40
	v_mul_f32_e32 v137, v143, v41
	v_mul_f32_e32 v138, v143, v42
	v_mul_f32_e32 v139, v143, v43
	v_fma_f32 v136, v136, v72, v104
	v_fma_f32 v137, v137, v73, v105
	v_fma_f32 v138, v138, v74, v106
	v_fma_f32 v139, v139, v75, v107
	v_cvt_pk_bf16_f32 v132, v136, v137
	v_cvt_pk_bf16_f32 v133, v138, v139
	global_store_dwordx2 v130, v[132:133], s[14:15] offset:1024
	v_mul_f32_e32 v136, v143, v44
	v_mul_f32_e32 v137, v143, v45
	v_mul_f32_e32 v138, v143, v46
	v_mul_f32_e32 v139, v143, v47
	v_fma_f32 v136, v136, v76, v108
	v_fma_f32 v137, v137, v77, v109
	v_fma_f32 v138, v138, v78, v110
	v_fma_f32 v139, v139, v79, v111
	v_cvt_pk_bf16_f32 v134, v136, v137
	v_cvt_pk_bf16_f32 v135, v138, v139
	global_store_dwordx2 v130, v[134:135], s[14:15] offset:1536
	v_mul_f32_e32 v136, v143, v48
; __device__ __forceinline__ unsigned cvt_pk_bf16(float lo, float hi) { unsigned r; asm volatile("v_cvt_pk_bf16_f32 %0, %1, %2" : "=v"(r) : "v"(lo), "v"(hi)); return r; }
; __device__ __forceinline__ void modulate_store(const f32x4 (&v)[8], float rstd, const float* pn, const float* modr, bf16_t* orow, int lane) {
; #pragma unroll
;     for (int j = 0; j < 8; ++j) { const int col = 4 * lane + 256 * j;
;         const f32x4 g = *(const f32x4*)(pn + col), sh = *(const f32x4*)(modr + col), sc = *(const f32x4*)(modr + DM + col);
;         const f32x4 hh = v[j] * rstd * g * (sc + 1.f) + sh;
;         u32x2 w; w.x = cvt_pk_bf16(hh[0], hh[1]); w.y = cvt_pk_bf16(hh[2], hh[3]);
;         *(u32x2*)(orow + col) = w; }
; }
; __global__ void __launch_bounds__(NWAVES * 64, 2) mk_fwd(Args args) {
;     ...
;         for (int row0 = F.gw * 3; row0 < MT; row0 += F.NGW * 3) {
;             f32x4 v[3][8];
; #pragma unroll
;             for (int q = 0; q < 3; ++q) { const int row = row0 + q; const float* src = row < ML ? x + (size_t)row * DM : ctx + (size_t)(row - ML) * DM; load_row_f32(src, F.lane, v[q]); }
; #pragma unroll
;             for (int q = 0; q < 3; ++q) { const int row = row0 + q; const int r = row < ML ? row / SEQ : 8;
;                 const float rstd = __builtin_amdgcn_rsqf(sumsq8(v[q]) * (1.f / DM) + EPS);
;                 modulate_store(v[q], rstd, pre_norm, mod + (size_t)r * 6144, H + (size_t)row * DM, F.lane); }
;         }
	v_mul_f32_e32 v137, v143, v49
	v_mul_f32_e32 v138, v143, v50
	v_mul_f32_e32 v139, v143, v51
	v_fma_f32 v136, v136, v80, v112
	v_fma_f32 v137, v137, v81, v113
	v_fma_f32 v138, v138, v82, v114
	v_fma_f32 v139, v139, v83, v115
	v_cvt_pk_bf16_f32 v132, v136, v137
	v_cvt_pk_bf16_f32 v133, v138, v139
	global_store_dwordx2 v130, v[132:133], s[14:15] offset:2048
	v_mul_f32_e32 v136, v143, v52
	v_mul_f32_e32 v137, v143, v53
	v_mul_f32_e32 v138, v143, v54
	v_mul_f32_e32 v139, v143, v55
	v_fma_f32 v136, v136, v84, v116
	v_fma_f32 v137, v137, v85, v117
	v_fma_f32 v138, v138, v86, v118
	v_fma_f32 v139, v139, v87, v119
	v_cvt_pk_bf16_f32 v134, v136, v137
	v_cvt_pk_bf16_f32 v135, v138, v139
	global_store_dwordx2 v130, v[134:135], s[14:15] offset:2560
	v_mul_f32_e32 v136, v143, v56
	v_mul_f32_e32 v137, v143, v57
	v_mul_f32_e32 v138, v143, v58
	v_mul_f32_e32 v139, v143, v59
	v_fma_f32 v136, v136, v88, v120
	v_fma_f32 v137, v137, v89, v121
	v_fma_f32 v138, v138, v90, v122
	v_fma_f32 v139, v139, v91, v123
	v_cvt_pk_bf16_f32 v132, v136, v137
	v_cvt_pk_bf16_f32 v133, v138, v139
	global_store_dwordx2 v130, v[132:133], s[14:15] offset:3072
	v_mul_f32_e32 v136, v143, v60
	v_mul_f32_e32 v137, v143, v61
	v_mul_f32_e32 v138, v143, v62
	v_mul_f32_e32 v139, v143, v63
	v_fma_f32 v136, v136, v92, v124
	v_fma_f32 v137, v137, v93, v125
	v_fma_f32 v138, v138, v94, v126
	v_fma_f32 v139, v139, v95, v127
	v_cvt_pk_bf16_f32 v134, v136, v137
	v_cvt_pk_bf16_f32 v135, v138, v139
	global_store_dwordx2 v130, v[134:135], s[14:15] offset:3584
	s_add_i32 s4, s6, 7
	s_cmp_lt_u32 s4, 0x4000
	s_cselect_b32 s10, s68, s72
	s_cselect_b32 s11, s69, s73
	s_cselect_b32 s5, 0, 0x4000
	s_sub_i32 s5, s4, s5
	s_lshl_b32 s5, s5, 13
	s_add_u32 s10, s10, s5
	s_addc_u32 s11, s11, 0
	global_load_dwordx4 v[32:35], v128, s[10:11] offset:0 nt
	global_load_dwordx4 v[36:39], v128, s[10:11] offset:1024 nt
	global_load_dwordx4 v[40:43], v128, s[10:11] offset:2048 nt
	global_load_dwordx4 v[44:47], v128, s[10:11] offset:3072 nt
	global_load_dwordx4 v[48:51], v129, s[10:11] offset:0 nt
	global_load_dwordx4 v[52:55], v129, s[10:11] offset:1024 nt
	global_load_dwordx4 v[56:59], v129, s[10:11] offset:2048 nt
	global_load_dwordx4 v[60:63], v129, s[10:11] offset:3072 nt
	s_add_i32 s4, s6, 6
	s_add_i32 s4, s6, 6
	s_lshr_b32 s8, s4, 11
	s_cmp_lt_u32 s4, 0x4000
	s_cselect_b32 s8, s8, 8
	s_cmp_eq_u32 s8, s7
	s_cbranch_scc1 .Lp1_np6
	s_mov_b32 s7, s8
	s_add_i32 s5, s8, 0
	s_mul_i32 s5, s5, 0x6000
	s_add_u32 s24, s84, s5
	s_addc_u32 s25, s85, 0
	s_add_u32 s24, s24, 0x2000
	s_addc_u32 s25, s25, 0
	s_add_i32 s5, s8, 0
	s_mul_i32 s5, s5, 0x6000
	s_add_u32 s16, s84, s5
	s_addc_u32 s17, s85, 0
	s_add_u32 s18, s80, 0x0
	s_addc_u32 s19, s81, 0
	global_load_dwordx4 v[64:67], v128, s[18:19] offset:0
	global_load_dwordx4 v[96:99], v128, s[16:17] offset:0
	global_load_dwordx4 v[68:71], v128, s[18:19] offset:1024
	global_load_dwordx4 v[100:103], v128, s[16:17] offset:1024
	global_load_dwordx4 v[72:75], v128, s[18:19] offset:2048
	global_load_dwordx4 v[104:107], v128, s[16:17] offset:2048
	global_load_dwordx4 v[76:79], v128, s[18:19] offset:3072
	global_load_dwordx4 v[108:111], v128, s[16:17] offset:3072
	global_load_dwordx4 v[80:83], v129, s[18:19] offset:0
	global_load_dwordx4 v[112:115], v129, s[16:17] offset:0
	global_load_dwordx4 v[84:87], v129, s[18:19] offset:1024
	global_load_dwordx4 v[116:119], v129, s[16:17] offset:1024
	global_load_dwordx4 v[88:91], v129, s[18:19] offset:2048
	global_load_dwordx4 v[120:123], v129, s[16:17] offset:2048
	global_load_dwordx4 v[92:95], v129, s[18:19] offset:3072
	global_load_dwordx4 v[124:127], v129, s[16:17] offset:3072
	global_load_dwordx4 v[136:139], v128, s[24:25] offset:0
	s_waitcnt vmcnt(0)
	v_add_f32_e32 v136, 1.0, v136
	v_add_f32_e32 v137, 1.0, v137
	v_add_f32_e32 v138, 1.0, v138
	v_add_f32_e32 v139, 1.0, v139
	v_mul_f32_e32 v64, v64, v136
	v_mul_f32_e32 v65, v65, v137
	v_mul_f32_e32 v66, v66, v138
	v_mul_f32_e32 v67, v67, v139
	global_load_dwordx4 v[136:139], v128, s[24:25] offset:1024
	s_waitcnt vmcnt(0)
	v_add_f32_e32 v136, 1.0, v136
	v_add_f32_e32 v137, 1.0, v137
	v_add_f32_e32 v138, 1.0, v138
	v_add_f32_e32 v139, 1.0, v139
	v_mul_f32_e32 v68, v68, v136
	v_mul_f32_e32 v69, v69, v137
	v_mul_f32_e32 v70, v70, v138
	v_mul_f32_e32 v71, v71, v139
	global_load_dwordx4 v[136:139], v128, s[24:25] offset:2048
	s_waitcnt vmcnt(0)
	v_add_f32_e32 v136, 1.0, v136
	v_add_f32_e32 v137, 1.0, v137
	v_add_f32_e32 v138, 1.0, v138
	v_add_f32_e32 v139, 1.0, v139
	v_mul_f32_e32 v72, v72, v136
	v_mul_f32_e32 v73, v73, v137
	v_mul_f32_e32 v74, v74, v138
	v_mul_f32_e32 v75, v75, v139
	global_load_dwordx4 v[136:139], v128, s[24:25] offset:3072
	s_waitcnt vmcnt(0)
	v_add_f32_e32 v136, 1.0, v136
	v_add_f32_e32 v137, 1.0, v137
	v_add_f32_e32 v138, 1.0, v138
	v_add_f32_e32 v139, 1.0, v139
	v_mul_f32_e32 v76, v76, v136
	v_mul_f32_e32 v77, v77, v137
	v_mul_f32_e32 v78, v78, v138
	v_mul_f32_e32 v79, v79, v139
	global_load_dwordx4 v[136:139], v129, s[24:25] offset:0
	s_waitcnt vmcnt(0)
	v_add_f32_e32 v136, 1.0, v136
	v_add_f32_e32 v137, 1.0, v137
	v_add_f32_e32 v138, 1.0, v138
	v_add_f32_e32 v139, 1.0, v139
	v_mul_f32_e32 v80, v80, v136
	v_mul_f32_e32 v81, v81, v137
	v_mul_f32_e32 v82, v82, v138
	v_mul_f32_e32 v83, v83, v139
	global_load_dwordx4 v[136:139], v129, s[24:25] offset:1024
	s_waitcnt vmcnt(0)
	v_add_f32_e32 v136, 1.0, v136
	v_add_f32_e32 v137, 1.0, v137
	v_add_f32_e32 v138, 1.0, v138
	v_add_f32_e32 v139, 1.0, v139
	v_mul_f32_e32 v84, v84, v136
	v_mul_f32_e32 v85, v85, v137
	v_mul_f32_e32 v86, v86, v138
	v_mul_f32_e32 v87, v87, v139
	global_load_dwordx4 v[136:139], v129, s[24:25] offset:2048
	s_waitcnt vmcnt(0)
	v_add_f32_e32 v136, 1.0, v136
	v_add_f32_e32 v137, 1.0, v137
	v_add_f32_e32 v138, 1.0, v138
	v_add_f32_e32 v139, 1.0, v139
	v_mul_f32_e32 v88, v88, v136
	v_mul_f32_e32 v89, v89, v137
	v_mul_f32_e32 v90, v90, v138
	v_mul_f32_e32 v91, v91, v139
	global_load_dwordx4 v[136:139], v129, s[24:25] offset:3072
	s_waitcnt vmcnt(0)
	v_add_f32_e32 v136, 1.0, v136
	v_add_f32_e32 v137, 1.0, v137
	v_add_f32_e32 v138, 1.0, v138
	v_add_f32_e32 v139, 1.0, v139
	v_mul_f32_e32 v92, v92, v136
	v_mul_f32_e32 v93, v93, v137
	v_mul_f32_e32 v94, v94, v138
	v_mul_f32_e32 v95, v95, v139
; __device__ __forceinline__ unsigned cvt_pk_bf16(float lo, float hi) { unsigned r; asm volatile("v_cvt_pk_bf16_f32 %0, %1, %2" : "=v"(r) : "v"(lo), "v"(hi)); return r; }
; __device__ __forceinline__ void load_row_f32(const float* p, int lane, f32x4 (&v)[8]) {
; #pragma unroll
;     for (int j = 0; j < 8; ++j) v[j] = *(const f32x4*)(p + 4 * lane + 256 * j);
; }
; __device__ __forceinline__ float sumsq8(const f32x4 (&v)[8]) {
;     float s = 0.f;
; #pragma unroll
;     for (int j = 0; j < 8; ++j) s += (v[j][0] * v[j][0] + v[j][1] * v[j][1]) + (v[j][2] * v[j][2] + v[j][3] * v[j][3]);
;     return wave_sum(s);
; }
; __device__ __forceinline__ void modulate_store(const f32x4 (&v)[8], float rstd, const float* pn, const float* modr, bf16_t* orow, int lane) {
; #pragma unroll
;     for (int j = 0; j < 8; ++j) { const int col = 4 * lane + 256 * j;
;         const f32x4 g = *(const f32x4*)(pn + col), sh = *(const f32x4*)(modr + col), sc = *(const f32x4*)(modr + DM + col);
;         const f32x4 hh = v[j] * rstd * g * (sc + 1.f) + sh;
;         u32x2 w; w.x = cvt_pk_bf16(hh[0], hh[1]); w.y = cvt_pk_bf16(hh[2], hh[3]);
;         *(u32x2*)(orow + col) = w; }
; }
; __global__ void __launch_bounds__(NWAVES * 64, 2) mk_fwd(Args args) {
;     ...
;         for (int row0 = F.gw * 3; row0 < MT; row0 += F.NGW * 3) {
;             f32x4 v[3][8];
; #pragma unroll
;             for (int q = 0; q < 3; ++q) { const int row = row0 + q; const float* src = row < ML ? x + (size_t)row * DM : ctx + (size_t)(row - ML) * DM; load_row_f32(src, F.lane, v[q]); }
; #pragma unroll
;             for (int q = 0; q < 3; ++q) { const int row = row0 + q; const int r = row < ML ? row / SEQ : 8;
;                 const float rstd = __builtin_amdgcn_rsqf(sumsq8(v[q]) * (1.f / DM) + EPS);
;                 modulate_store(v[q], rstd, pre_norm, mod + (size_t)r * 6144, H + (size_t)row * DM, F.lane); }
;         }
.Lp1_np6:
	s_waitcnt vmcnt(16)
	v_mul_f32_e32 v140, v0, v0
	v_mul_f32_e32 v141, v1, v1
	v_fmac_f32_e32 v140, v2, v2
	v_fmac_f32_e32 v141, v3, v3
	v_fmac_f32_e32 v140, v4, v4
	v_fmac_f32_e32 v141, v5, v5
	v_fmac_f32_e32 v140, v6, v6
	v_fmac_f32_e32 v141, v7, v7
	v_fmac_f32_e32 v140, v8, v8
	v_fmac_f32_e32 v141, v9, v9
	v_fmac_f32_e32 v140, v10, v10
	v_fmac_f32_e32 v141, v11, v11
	v_fmac_f32_e32 v140, v12, v12
	v_fmac_f32_e32 v141, v13, v13
	v_fmac_f32_e32 v140, v14, v14
	v_fmac_f32_e32 v141, v15, v15
	v_fmac_f32_e32 v140, v16, v16
	v_fmac_f32_e32 v141, v17, v17
	v_fmac_f32_e32 v140, v18, v18
	v_fmac_f32_e32 v141, v19, v19
	v_fmac_f32_e32 v140, v20, v20
	v_fmac_f32_e32 v141, v21, v21
	v_fmac_f32_e32 v140, v22, v22
	v_fmac_f32_e32 v141, v23, v23
	v_fmac_f32_e32 v140, v24, v24
	v_fmac_f32_e32 v141, v25, v25
	v_fmac_f32_e32 v140, v26, v26
	v_fmac_f32_e32 v141, v27, v27
	v_fmac_f32_e32 v140, v28, v28
	v_fmac_f32_e32 v141, v29, v29
	v_fmac_f32_e32 v140, v30, v30
	v_fmac_f32_e32 v141, v31, v31
	v_add_f32_e32 v140, v140, v141
	s_nop 1
	v_add_f32_dpp v142, v140, v140 quad_perm:[1,0,3,2] row_mask:0xf bank_mask:0xf
	s_nop 1
	v_add_f32_dpp v142, v142, v142 quad_perm:[2,3,0,1] row_mask:0xf bank_mask:0xf
	s_nop 1
	v_add_f32_dpp v142, v142, v142 row_half_mirror row_mask:0xf bank_mask:0xf
	s_nop 1
	v_add_f32_dpp v142, v142, v142 row_mirror row_mask:0xf bank_mask:0xf
	s_nop 1
	v_readlane_b32 s20, v142, 0
	v_readlane_b32 s21, v142, 16
	v_readlane_b32 s22, v142, 32
	v_readlane_b32 s23, v142, 48
	s_nop 1
	v_mov_b32_e32 v143, s20
	v_add_f32_e32 v143, s21, v143
	v_add_f32_e32 v143, s22, v143
	v_add_f32_e32 v143, s23, v143
	v_fmamk_f32 v143, v143, 0x3a000000, v131
	v_rsq_f32_e32 v143, v143
	s_nop 0
	s_add_i32 s4, s6, 6
	s_lshl_b32 s5, s4, 12
	s_add_u32 s14, s84, s5
	s_addc_u32 s15, s85, 0
	s_add_u32 s14, s14, 0x11800000
	s_addc_u32 s15, s15, 0
	v_mul_f32_e32 v136, v143, v0
	v_mul_f32_e32 v137, v143, v1
	v_mul_f32_e32 v138, v143, v2
	v_mul_f32_e32 v139, v143, v3
	v_fma_f32 v136, v136, v64, v96
	v_fma_f32 v137, v137, v65, v97
	v_fma_f32 v138, v138, v66, v98
	v_fma_f32 v139, v139, v67, v99
	v_cvt_pk_bf16_f32 v132, v136, v137
	v_cvt_pk_bf16_f32 v133, v138, v139
	global_store_dwordx2 v130, v[132:133], s[14:15] offset:0
	v_mul_f32_e32 v136, v143, v4
	v_mul_f32_e32 v137, v143, v5
	v_mul_f32_e32 v138, v143, v6
	v_mul_f32_e32 v139, v143, v7
	v_fma_f32 v136, v136, v68, v100
	v_fma_f32 v137, v137, v69, v101
	v_fma_f32 v138, v138, v70, v102
	v_fma_f32 v139, v139, v71, v103
	v_cvt_pk_bf16_f32 v134, v136, v137
	v_cvt_pk_bf16_f32 v135, v138, v139
	global_store_dwordx2 v130, v[134:135], s[14:15] offset:512
	v_mul_f32_e32 v136, v143, v8
	v_mul_f32_e32 v137, v143, v9
	v_mul_f32_e32 v138, v143, v10
	v_mul_f32_e32 v139, v143, v11
	v_fma_f32 v136, v136, v72, v104
	v_fma_f32 v137, v137, v73, v105
	v_fma_f32 v138, v138, v74, v106
	v_fma_f32 v139, v139, v75, v107
	v_cvt_pk_bf16_f32 v132, v136, v137
	v_cvt_pk_bf16_f32 v133, v138, v139
	global_store_dwordx2 v130, v[132:133], s[14:15] offset:1024
	v_mul_f32_e32 v136, v143, v12
	v_mul_f32_e32 v137, v143, v13
	v_mul_f32_e32 v138, v143, v14
	v_mul_f32_e32 v139, v143, v15
	v_fma_f32 v136, v136, v76, v108
	v_fma_f32 v137, v137, v77, v109
	v_fma_f32 v138, v138, v78, v110
	v_fma_f32 v139, v139, v79, v111
	v_cvt_pk_bf16_f32 v134, v136, v137
	v_cvt_pk_bf16_f32 v135, v138, v139
	global_store_dwordx2 v130, v[134:135], s[14:15] offset:1536
	v_mul_f32_e32 v136, v143, v16
	v_mul_f32_e32 v137, v143, v17
	v_mul_f32_e32 v138, v143, v18
	v_mul_f32_e32 v139, v143, v19
	v_fma_f32 v136, v136, v80, v112
	v_fma_f32 v137, v137, v81, v113
	v_fma_f32 v138, v138, v82, v114
	v_fma_f32 v139, v139, v83, v115
	v_cvt_pk_bf16_f32 v132, v136, v137
	v_cvt_pk_bf16_f32 v133, v138, v139
	global_store_dwordx2 v130, v[132:133], s[14:15] offset:2048
	v_mul_f32_e32 v136, v143, v20
	v_mul_f32_e32 v137, v143, v21
	v_mul_f32_e32 v138, v143, v22
	v_mul_f32_e32 v139, v143, v23
	v_fma_f32 v136, v136, v84, v116
	v_fma_f32 v137, v137, v85, v117
	v_fma_f32 v138, v138, v86, v118
	v_fma_f32 v139, v139, v87, v119
	v_cvt_pk_bf16_f32 v134, v136, v137
	v_cvt_pk_bf16_f32 v135, v138, v139
	global_store_dwordx2 v130, v[134:135], s[14:15] offset:2560
	v_mul_f32_e32 v136, v143, v24
	v_mul_f32_e32 v137, v143, v25
	v_mul_f32_e32 v138, v143, v26
	v_mul_f32_e32 v139, v143, v27
	v_fma_f32 v136, v136, v88, v120
	v_fma_f32 v137, v137, v89, v121
	v_fma_f32 v138, v138, v90, v122
	v_fma_f32 v139, v139, v91, v123
	v_cvt_pk_bf16_f32 v132, v136, v137
	v_cvt_pk_bf16_f32 v133, v138, v139
	global_store_dwordx2 v130, v[132:133], s[14:15] offset:3072
	v_mul_f32_e32 v136, v143, v28
	v_mul_f32_e32 v137, v143, v29
	v_mul_f32_e32 v138, v143, v30
	v_mul_f32_e32 v139, v143, v31
	v_fma_f32 v136, v136, v92, v124
	v_fma_f32 v137, v137, v93, v125
	v_fma_f32 v138, v138, v94, v126
	v_fma_f32 v139, v139, v95, v127
	v_cvt_pk_bf16_f32 v134, v136, v137
	v_cvt_pk_bf16_f32 v135, v138, v139
	global_store_dwordx2 v130, v[134:135], s[14:15] offset:3584
	s_add_i32 s4, s6, 8
	s_cmp_lt_u32 s4, 0x4000
	s_cselect_b32 s10, s68, s72
	s_cselect_b32 s11, s69, s73
	s_cselect_b32 s5, 0, 0x4000
	s_sub_i32 s5, s4, s5
	s_lshl_b32 s5, s5, 13
	s_add_u32 s10, s10, s5
	s_addc_u32 s11, s11, 0
	global_load_dwordx4 v[0:3], v128, s[10:11] offset:0 nt
	global_load_dwordx4 v[4:7], v128, s[10:11] offset:1024 nt
	global_load_dwordx4 v[8:11], v128, s[10:11] offset:2048 nt
	global_load_dwordx4 v[12:15], v128, s[10:11] offset:3072 nt
	global_load_dwordx4 v[16:19], v129, s[10:11] offset:0 nt
	global_load_dwordx4 v[20:23], v129, s[10:11] offset:1024 nt
	global_load_dwordx4 v[24:27], v129, s[10:11] offset:2048 nt
	global_load_dwordx4 v[28:31], v129, s[10:11] offset:3072 nt
	s_add_i32 s4, s6, 7
	s_add_i32 s4, s6, 7
	s_lshr_b32 s8, s4, 11
	s_cmp_lt_u32 s4, 0x4000
	s_cselect_b32 s8, s8, 8
	s_cmp_eq_u32 s8, s7
	s_cbranch_scc1 .Lp1_np7
; __device__ __forceinline__ unsigned cvt_pk_bf16(float lo, float hi) { unsigned r; asm volatile("v_cvt_pk_bf16_f32 %0, %1, %2" : "=v"(r) : "v"(lo), "v"(hi)); return r; }
; __device__ __forceinline__ void modulate_store(const f32x4 (&v)[8], float rstd, const float* pn, const float* modr, bf16_t* orow, int lane) {
; #pragma unroll
;     for (int j = 0; j < 8; ++j) { const int col = 4 * lane + 256 * j;
;         const f32x4 g = *(const f32x4*)(pn + col), sh = *(const f32x4*)(modr + col), sc = *(const f32x4*)(modr + DM + col);
;         const f32x4 hh = v[j] * rstd * g * (sc + 1.f) + sh;
;         u32x2 w; w.x = cvt_pk_bf16(hh[0], hh[1]); w.y = cvt_pk_bf16(hh[2], hh[3]);
;         *(u32x2*)(orow + col) = w; }
; }
; __global__ void __launch_bounds__(NWAVES * 64, 2) mk_fwd(Args args) {
;     ...
;         for (int row0 = F.gw * 3; row0 < MT; row0 += F.NGW * 3) {
;             f32x4 v[3][8];
; #pragma unroll
;             for (int q = 0; q < 3; ++q) { const int row = row0 + q; const float* src = row < ML ? x + (size_t)row * DM : ctx + (size_t)(row - ML) * DM; load_row_f32(src, F.lane, v[q]); }
; #pragma unroll
;             for (int q = 0; q < 3; ++q) { const int row = row0 + q; const int r = row < ML ? row / SEQ : 8;
;                 const float rstd = __builtin_amdgcn_rsqf(sumsq8(v[q]) * (1.f / DM) + EPS);
;                 modulate_store(v[q], rstd, pre_norm, mod + (size_t)r * 6144, H + (size_t)row * DM, F.lane); }
;         }
	s_mov_b32 s7, s8
	s_add_i32 s5, s8, 0
	s_mul_i32 s5, s5, 0x6000
	s_add_u32 s24, s84, s5
	s_addc_u32 s25, s85, 0
	s_add_u32 s24, s24, 0x2000
	s_addc_u32 s25, s25, 0
	s_add_i32 s5, s8, 0
	s_mul_i32 s5, s5, 0x6000
	s_add_u32 s16, s84, s5
	s_addc_u32 s17, s85, 0
	s_add_u32 s18, s80, 0x0
	s_addc_u32 s19, s81, 0
	global_load_dwordx4 v[64:67], v128, s[18:19] offset:0
	global_load_dwordx4 v[96:99], v128, s[16:17] offset:0
	global_load_dwordx4 v[68:71], v128, s[18:19] offset:1024
	global_load_dwordx4 v[100:103], v128, s[16:17] offset:1024
	global_load_dwordx4 v[72:75], v128, s[18:19] offset:2048
	global_load_dwordx4 v[104:107], v128, s[16:17] offset:2048
	global_load_dwordx4 v[76:79], v128, s[18:19] offset:3072
	global_load_dwordx4 v[108:111], v128, s[16:17] offset:3072
	global_load_dwordx4 v[80:83], v129, s[18:19] offset:0
	global_load_dwordx4 v[112:115], v129, s[16:17] offset:0
	global_load_dwordx4 v[84:87], v129, s[18:19] offset:1024
	global_load_dwordx4 v[116:119], v129, s[16:17] offset:1024
	global_load_dwordx4 v[88:91], v129, s[18:19] offset:2048
	global_load_dwordx4 v[120:123], v129, s[16:17] offset:2048
	global_load_dwordx4 v[92:95], v129, s[18:19] offset:3072
	global_load_dwordx4 v[124:127], v129, s[16:17] offset:3072
	global_load_dwordx4 v[136:139], v128, s[24:25] offset:0
	s_waitcnt vmcnt(0)
	v_add_f32_e32 v136, 1.0, v136
	v_add_f32_e32 v137, 1.0, v137
	v_add_f32_e32 v138, 1.0, v138
	v_add_f32_e32 v139, 1.0, v139
	v_mul_f32_e32 v64, v64, v136
	v_mul_f32_e32 v65, v65, v137
	v_mul_f32_e32 v66, v66, v138
	v_mul_f32_e32 v67, v67, v139
	global_load_dwordx4 v[136:139], v128, s[24:25] offset:1024
	s_waitcnt vmcnt(0)
	v_add_f32_e32 v136, 1.0, v136
	v_add_f32_e32 v137, 1.0, v137
	v_add_f32_e32 v138, 1.0, v138
	v_add_f32_e32 v139, 1.0, v139
	v_mul_f32_e32 v68, v68, v136
	v_mul_f32_e32 v69, v69, v137
	v_mul_f32_e32 v70, v70, v138
	v_mul_f32_e32 v71, v71, v139
	global_load_dwordx4 v[136:139], v128, s[24:25] offset:2048
	s_waitcnt vmcnt(0)
	v_add_f32_e32 v136, 1.0, v136
	v_add_f32_e32 v137, 1.0, v137
	v_add_f32_e32 v138, 1.0, v138
	v_add_f32_e32 v139, 1.0, v139
	v_mul_f32_e32 v72, v72, v136
	v_mul_f32_e32 v73, v73, v137
	v_mul_f32_e32 v74, v74, v138
	v_mul_f32_e32 v75, v75, v139
	global_load_dwordx4 v[136:139], v128, s[24:25] offset:3072
	s_waitcnt vmcnt(0)
	v_add_f32_e32 v136, 1.0, v136
	v_add_f32_e32 v137, 1.0, v137
	v_add_f32_e32 v138, 1.0, v138
	v_add_f32_e32 v139, 1.0, v139
	v_mul_f32_e32 v76, v76, v136
	v_mul_f32_e32 v77, v77, v137
	v_mul_f32_e32 v78, v78, v138
	v_mul_f32_e32 v79, v79, v139
	global_load_dwordx4 v[136:139], v129, s[24:25] offset:0
	s_waitcnt vmcnt(0)
	v_add_f32_e32 v136, 1.0, v136
	v_add_f32_e32 v137, 1.0, v137
	v_add_f32_e32 v138, 1.0, v138
	v_add_f32_e32 v139, 1.0, v139
	v_mul_f32_e32 v80, v80, v136
	v_mul_f32_e32 v81, v81, v137
	v_mul_f32_e32 v82, v82, v138
	v_mul_f32_e32 v83, v83, v139
	global_load_dwordx4 v[136:139], v129, s[24:25] offset:1024
	s_waitcnt vmcnt(0)
	v_add_f32_e32 v136, 1.0, v136
	v_add_f32_e32 v137, 1.0, v137
	v_add_f32_e32 v138, 1.0, v138
	v_add_f32_e32 v139, 1.0, v139
	v_mul_f32_e32 v84, v84, v136
	v_mul_f32_e32 v85, v85, v137
	v_mul_f32_e32 v86, v86, v138
	v_mul_f32_e32 v87, v87, v139
	global_load_dwordx4 v[136:139], v129, s[24:25] offset:2048
	s_waitcnt vmcnt(0)
	v_add_f32_e32 v136, 1.0, v136
	v_add_f32_e32 v137, 1.0, v137
	v_add_f32_e32 v138, 1.0, v138
	v_add_f32_e32 v139, 1.0, v139
	v_mul_f32_e32 v88, v88, v136
	v_mul_f32_e32 v89, v89, v137
	v_mul_f32_e32 v90, v90, v138
	v_mul_f32_e32 v91, v91, v139
	global_load_dwordx4 v[136:139], v129, s[24:25] offset:3072
	s_waitcnt vmcnt(0)
	v_add_f32_e32 v136, 1.0, v136
	v_add_f32_e32 v137, 1.0, v137
	v_add_f32_e32 v138, 1.0, v138
	v_add_f32_e32 v139, 1.0, v139
	v_mul_f32_e32 v92, v92, v136
	v_mul_f32_e32 v93, v93, v137
	v_mul_f32_e32 v94, v94, v138
	v_mul_f32_e32 v95, v95, v139
.Lp1_np7:
	s_waitcnt vmcnt(16)
	v_mul_f32_e32 v140, v32, v32
	v_mul_f32_e32 v141, v33, v33
	v_fmac_f32_e32 v140, v34, v34
	v_fmac_f32_e32 v141, v35, v35
	v_fmac_f32_e32 v140, v36, v36
	v_fmac_f32_e32 v141, v37, v37
	v_fmac_f32_e32 v140, v38, v38
	v_fmac_f32_e32 v141, v39, v39
	v_fmac_f32_e32 v140, v40, v40
	v_fmac_f32_e32 v141, v41, v41
	v_fmac_f32_e32 v140, v42, v42
	v_fmac_f32_e32 v141, v43, v43
	v_fmac_f32_e32 v140, v44, v44
	v_fmac_f32_e32 v141, v45, v45
	v_fmac_f32_e32 v140, v46, v46
	v_fmac_f32_e32 v141, v47, v47
	v_fmac_f32_e32 v140, v48, v48
	v_fmac_f32_e32 v141, v49, v49
	v_fmac_f32_e32 v140, v50, v50
	v_fmac_f32_e32 v141, v51, v51
	v_fmac_f32_e32 v140, v52, v52
	v_fmac_f32_e32 v141, v53, v53
	v_fmac_f32_e32 v140, v54, v54
	v_fmac_f32_e32 v141, v55, v55
	v_fmac_f32_e32 v140, v56, v56
	v_fmac_f32_e32 v141, v57, v57
	v_fmac_f32_e32 v140, v58, v58
	v_fmac_f32_e32 v141, v59, v59
	v_fmac_f32_e32 v140, v60, v60
	v_fmac_f32_e32 v141, v61, v61
	v_fmac_f32_e32 v140, v62, v62
	v_fmac_f32_e32 v141, v63, v63
	v_add_f32_e32 v140, v140, v141
	s_nop 1
	v_add_f32_dpp v142, v140, v140 quad_perm:[1,0,3,2] row_mask:0xf bank_mask:0xf
	s_nop 1
	v_add_f32_dpp v142, v142, v142 quad_perm:[2,3,0,1] row_mask:0xf bank_mask:0xf
	s_nop 1
	v_add_f32_dpp v142, v142, v142 row_half_mirror row_mask:0xf bank_mask:0xf
	s_nop 1
	v_add_f32_dpp v142, v142, v142 row_mirror row_mask:0xf bank_mask:0xf
	s_nop 1
	v_readlane_b32 s20, v142, 0
	v_readlane_b32 s21, v142, 16
	v_readlane_b32 s22, v142, 32
	v_readlane_b32 s23, v142, 48
	s_nop 1
	v_mov_b32_e32 v143, s20
	v_add_f32_e32 v143, s21, v143
	v_add_f32_e32 v143, s22, v143
	v_add_f32_e32 v143, s23, v143
	v_fmamk_f32 v143, v143, 0x3a000000, v131
	v_rsq_f32_e32 v143, v143
	s_nop 0
	s_add_i32 s4, s6, 7
	s_lshl_b32 s5, s4, 12
	s_add_u32 s14, s84, s5
	s_addc_u32 s15, s85, 0
; __device__ __forceinline__ unsigned cvt_pk_bf16(float lo, float hi) { unsigned r; asm volatile("v_cvt_pk_bf16_f32 %0, %1, %2" : "=v"(r) : "v"(lo), "v"(hi)); return r; }
; __device__ __forceinline__ void modulate_store(const f32x4 (&v)[8], float rstd, const float* pn, const float* modr, bf16_t* orow, int lane) {
; #pragma unroll
;     for (int j = 0; j < 8; ++j) { const int col = 4 * lane + 256 * j;
;         const f32x4 g = *(const f32x4*)(pn + col), sh = *(const f32x4*)(modr + col), sc = *(const f32x4*)(modr + DM + col);
;         const f32x4 hh = v[j] * rstd * g * (sc + 1.f) + sh;
;         u32x2 w; w.x = cvt_pk_bf16(hh[0], hh[1]); w.y = cvt_pk_bf16(hh[2], hh[3]);
;         *(u32x2*)(orow + col) = w; }
; }
; __global__ void __launch_bounds__(NWAVES * 64, 2) mk_fwd(Args args) {
;     ...
;         for (int row0 = F.gw * 3; row0 < MT; row0 += F.NGW * 3) {
;             f32x4 v[3][8];
; #pragma unroll
;             for (int q = 0; q < 3; ++q) { const int row = row0 + q; const float* src = row < ML ? x + (size_t)row * DM : ctx + (size_t)(row - ML) * DM; load_row_f32(src, F.lane, v[q]); }
; #pragma unroll
;             for (int q = 0; q < 3; ++q) { const int row = row0 + q; const int r = row < ML ? row / SEQ : 8;
;                 const float rstd = __builtin_amdgcn_rsqf(sumsq8(v[q]) * (1.f / DM) + EPS);
;                 modulate_store(v[q], rstd, pre_norm, mod + (size_t)r * 6144, H + (size_t)row * DM, F.lane); }
;         }
	s_add_u32 s14, s14, 0x11800000
	s_addc_u32 s15, s15, 0
	v_mul_f32_e32 v136, v143, v32
	v_mul_f32_e32 v137, v143, v33
	v_mul_f32_e32 v138, v143, v34
	v_mul_f32_e32 v139, v143, v35
	v_fma_f32 v136, v136, v64, v96
	v_fma_f32 v137, v137, v65, v97
	v_fma_f32 v138, v138, v66, v98
	v_fma_f32 v139, v139, v67, v99
	v_cvt_pk_bf16_f32 v132, v136, v137
	v_cvt_pk_bf16_f32 v133, v138, v139
	global_store_dwordx2 v130, v[132:133], s[14:15] offset:0
	v_mul_f32_e32 v136, v143, v36
	v_mul_f32_e32 v137, v143, v37
	v_mul_f32_e32 v138, v143, v38
	v_mul_f32_e32 v139, v143, v39
	v_fma_f32 v136, v136, v68, v100
	v_fma_f32 v137, v137, v69, v101
	v_fma_f32 v138, v138, v70, v102
	v_fma_f32 v139, v139, v71, v103
	v_cvt_pk_bf16_f32 v134, v136, v137
	v_cvt_pk_bf16_f32 v135, v138, v139
	global_store_dwordx2 v130, v[134:135], s[14:15] offset:512
	v_mul_f32_e32 v136, v143, v40
	v_mul_f32_e32 v137, v143, v41
	v_mul_f32_e32 v138, v143, v42
	v_mul_f32_e32 v139, v143, v43
	v_fma_f32 v136, v136, v72, v104
	v_fma_f32 v137, v137, v73, v105
	v_fma_f32 v138, v138, v74, v106
	v_fma_f32 v139, v139, v75, v107
	v_cvt_pk_bf16_f32 v132, v136, v137
	v_cvt_pk_bf16_f32 v133, v138, v139
	global_store_dwordx2 v130, v[132:133], s[14:15] offset:1024
	v_mul_f32_e32 v136, v143, v44
	v_mul_f32_e32 v137, v143, v45
	v_mul_f32_e32 v138, v143, v46
	v_mul_f32_e32 v139, v143, v47
	v_fma_f32 v136, v136, v76, v108
	v_fma_f32 v137, v137, v77, v109
	v_fma_f32 v138, v138, v78, v110
	v_fma_f32 v139, v139, v79, v111
	v_cvt_pk_bf16_f32 v134, v136, v137
	v_cvt_pk_bf16_f32 v135, v138, v139
	global_store_dwordx2 v130, v[134:135], s[14:15] offset:1536
	v_mul_f32_e32 v136, v143, v48
	v_mul_f32_e32 v137, v143, v49
	v_mul_f32_e32 v138, v143, v50
	v_mul_f32_e32 v139, v143, v51
	v_fma_f32 v136, v136, v80, v112
	v_fma_f32 v137, v137, v81, v113
	v_fma_f32 v138, v138, v82, v114
	v_fma_f32 v139, v139, v83, v115
	v_cvt_pk_bf16_f32 v132, v136, v137
	v_cvt_pk_bf16_f32 v133, v138, v139
	global_store_dwordx2 v130, v[132:133], s[14:15] offset:2048
	v_mul_f32_e32 v136, v143, v52
	v_mul_f32_e32 v137, v143, v53
	v_mul_f32_e32 v138, v143, v54
	v_mul_f32_e32 v139, v143, v55
	v_fma_f32 v136, v136, v84, v116
	v_fma_f32 v137, v137, v85, v117
	v_fma_f32 v138, v138, v86, v118
	v_fma_f32 v139, v139, v87, v119
	v_cvt_pk_bf16_f32 v134, v136, v137
	v_cvt_pk_bf16_f32 v135, v138, v139
	global_store_dwordx2 v130, v[134:135], s[14:15] offset:2560
	v_mul_f32_e32 v136, v143, v56
	v_mul_f32_e32 v137, v143, v57
	v_mul_f32_e32 v138, v143, v58
	v_mul_f32_e32 v139, v143, v59
	v_fma_f32 v136, v136, v88, v120
	v_fma_f32 v137, v137, v89, v121
	v_fma_f32 v138, v138, v90, v122
	v_fma_f32 v139, v139, v91, v123
	v_cvt_pk_bf16_f32 v132, v136, v137
	v_cvt_pk_bf16_f32 v133, v138, v139
	global_store_dwordx2 v130, v[132:133], s[14:15] offset:3072
	v_mul_f32_e32 v136, v143, v60
	v_mul_f32_e32 v137, v143, v61
	v_mul_f32_e32 v138, v143, v62
	v_mul_f32_e32 v139, v143, v63
	v_fma_f32 v136, v136, v92, v124
	v_fma_f32 v137, v137, v93, v125
	v_fma_f32 v138, v138, v94, v126
	v_fma_f32 v139, v139, v95, v127
	v_cvt_pk_bf16_f32 v134, v136, v137
	v_cvt_pk_bf16_f32 v135, v138, v139
	global_store_dwordx2 v130, v[134:135], s[14:15] offset:3584
	s_add_i32 s4, s6, 8
	s_add_i32 s4, s6, 8
	s_lshr_b32 s8, s4, 11
	s_cmp_lt_u32 s4, 0x4000
	s_cselect_b32 s8, s8, 8
	s_cmp_eq_u32 s8, s7
	s_cbranch_scc1 .Lp1_np8
	s_mov_b32 s7, s8
	s_add_i32 s5, s8, 0
	s_mul_i32 s5, s5, 0x6000
	s_add_u32 s24, s84, s5
	s_addc_u32 s25, s85, 0
	s_add_u32 s24, s24, 0x2000
	s_addc_u32 s25, s25, 0
	s_add_i32 s5, s8, 0
	s_mul_i32 s5, s5, 0x6000
	s_add_u32 s16, s84, s5
	s_addc_u32 s17, s85, 0
	s_add_u32 s18, s80, 0x0
	s_addc_u32 s19, s81, 0
	global_load_dwordx4 v[64:67], v128, s[18:19] offset:0
	global_load_dwordx4 v[96:99], v128, s[16:17] offset:0
	global_load_dwordx4 v[68:71], v128, s[18:19] offset:1024
	global_load_dwordx4 v[100:103], v128, s[16:17] offset:1024
	global_load_dwordx4 v[72:75], v128, s[18:19] offset:2048
	global_load_dwordx4 v[104:107], v128, s[16:17] offset:2048
	global_load_dwordx4 v[76:79], v128, s[18:19] offset:3072
	global_load_dwordx4 v[108:111], v128, s[16:17] offset:3072
	global_load_dwordx4 v[80:83], v129, s[18:19] offset:0
	global_load_dwordx4 v[112:115], v129, s[16:17] offset:0
	global_load_dwordx4 v[84:87], v129, s[18:19] offset:1024
	global_load_dwordx4 v[116:119], v129, s[16:17] offset:1024
	global_load_dwordx4 v[88:91], v129, s[18:19] offset:2048
	global_load_dwordx4 v[120:123], v129, s[16:17] offset:2048
	global_load_dwordx4 v[92:95], v129, s[18:19] offset:3072
	global_load_dwordx4 v[124:127], v129, s[16:17] offset:3072
	global_load_dwordx4 v[136:139], v128, s[24:25] offset:0
	s_waitcnt vmcnt(0)
	v_add_f32_e32 v136, 1.0, v136
	v_add_f32_e32 v137, 1.0, v137
	v_add_f32_e32 v138, 1.0, v138
	v_add_f32_e32 v139, 1.0, v139
	v_mul_f32_e32 v64, v64, v136
	v_mul_f32_e32 v65, v65, v137
	v_mul_f32_e32 v66, v66, v138
	v_mul_f32_e32 v67, v67, v139
	global_load_dwordx4 v[136:139], v128, s[24:25] offset:1024
	s_waitcnt vmcnt(0)
	v_add_f32_e32 v136, 1.0, v136
	v_add_f32_e32 v137, 1.0, v137
	v_add_f32_e32 v138, 1.0, v138
	v_add_f32_e32 v139, 1.0, v139
	v_mul_f32_e32 v68, v68, v136
	v_mul_f32_e32 v69, v69, v137
	v_mul_f32_e32 v70, v70, v138
	v_mul_f32_e32 v71, v71, v139
	global_load_dwordx4 v[136:139], v128, s[24:25] offset:2048
	s_waitcnt vmcnt(0)
	v_add_f32_e32 v136, 1.0, v136
	v_add_f32_e32 v137, 1.0, v137
	v_add_f32_e32 v138, 1.0, v138
	v_add_f32_e32 v139, 1.0, v139
	v_mul_f32_e32 v72, v72, v136
	v_mul_f32_e32 v73, v73, v137
	v_mul_f32_e32 v74, v74, v138
	v_mul_f32_e32 v75, v75, v139
	global_load_dwordx4 v[136:139], v128, s[24:25] offset:3072
	s_waitcnt vmcnt(0)
; __device__ __forceinline__ unsigned cvt_pk_bf16(float lo, float hi) { unsigned r; asm volatile("v_cvt_pk_bf16_f32 %0, %1, %2" : "=v"(r) : "v"(lo), "v"(hi)); return r; }
; __device__ __forceinline__ void modulate_store(const f32x4 (&v)[8], float rstd, const float* pn, const float* modr, bf16_t* orow, int lane) {
; #pragma unroll
;     for (int j = 0; j < 8; ++j) { const int col = 4 * lane + 256 * j;
;         const f32x4 g = *(const f32x4*)(pn + col), sh = *(const f32x4*)(modr + col), sc = *(const f32x4*)(modr + DM + col);
;         const f32x4 hh = v[j] * rstd * g * (sc + 1.f) + sh;
;         u32x2 w; w.x = cvt_pk_bf16(hh[0], hh[1]); w.y = cvt_pk_bf16(hh[2], hh[3]);
;         *(u32x2*)(orow + col) = w; }
; }
; __global__ void __launch_bounds__(NWAVES * 64, 2) mk_fwd(Args args) {
;     ...
;         for (int row0 = F.gw * 3; row0 < MT; row0 += F.NGW * 3) {
;             f32x4 v[3][8];
; #pragma unroll
;             for (int q = 0; q < 3; ++q) { const int row = row0 + q; const float* src = row < ML ? x + (size_t)row * DM : ctx + (size_t)(row - ML) * DM; load_row_f32(src, F.lane, v[q]); }
; #pragma unroll
;             for (int q = 0; q < 3; ++q) { const int row = row0 + q; const int r = row < ML ? row / SEQ : 8;
;                 const float rstd = __builtin_amdgcn_rsqf(sumsq8(v[q]) * (1.f / DM) + EPS);
;                 modulate_store(v[q], rstd, pre_norm, mod + (size_t)r * 6144, H + (size_t)row * DM, F.lane); }
;         }
	v_add_f32_e32 v136, 1.0, v136
	v_add_f32_e32 v137, 1.0, v137
	v_add_f32_e32 v138, 1.0, v138
	v_add_f32_e32 v139, 1.0, v139
	v_mul_f32_e32 v76, v76, v136
	v_mul_f32_e32 v77, v77, v137
	v_mul_f32_e32 v78, v78, v138
	v_mul_f32_e32 v79, v79, v139
	global_load_dwordx4 v[136:139], v129, s[24:25] offset:0
	s_waitcnt vmcnt(0)
	v_add_f32_e32 v136, 1.0, v136
	v_add_f32_e32 v137, 1.0, v137
	v_add_f32_e32 v138, 1.0, v138
	v_add_f32_e32 v139, 1.0, v139
	v_mul_f32_e32 v80, v80, v136
	v_mul_f32_e32 v81, v81, v137
	v_mul_f32_e32 v82, v82, v138
	v_mul_f32_e32 v83, v83, v139
	global_load_dwordx4 v[136:139], v129, s[24:25] offset:1024
	s_waitcnt vmcnt(0)
	v_add_f32_e32 v136, 1.0, v136
	v_add_f32_e32 v137, 1.0, v137
	v_add_f32_e32 v138, 1.0, v138
	v_add_f32_e32 v139, 1.0, v139
	v_mul_f32_e32 v84, v84, v136
	v_mul_f32_e32 v85, v85, v137
	v_mul_f32_e32 v86, v86, v138
	v_mul_f32_e32 v87, v87, v139
	global_load_dwordx4 v[136:139], v129, s[24:25] offset:2048
	s_waitcnt vmcnt(0)
	v_add_f32_e32 v136, 1.0, v136
	v_add_f32_e32 v137, 1.0, v137
	v_add_f32_e32 v138, 1.0, v138
	v_add_f32_e32 v139, 1.0, v139
	v_mul_f32_e32 v88, v88, v136
	v_mul_f32_e32 v89, v89, v137
	v_mul_f32_e32 v90, v90, v138
	v_mul_f32_e32 v91, v91, v139
	global_load_dwordx4 v[136:139], v129, s[24:25] offset:3072
	s_waitcnt vmcnt(0)
	v_add_f32_e32 v136, 1.0, v136
	v_add_f32_e32 v137, 1.0, v137
	v_add_f32_e32 v138, 1.0, v138
	v_add_f32_e32 v139, 1.0, v139
	v_mul_f32_e32 v92, v92, v136
	v_mul_f32_e32 v93, v93, v137
	v_mul_f32_e32 v94, v94, v138
	v_mul_f32_e32 v95, v95, v139
.Lp1_np8:
	s_waitcnt vmcnt(8)
	v_mul_f32_e32 v140, v0, v0
	v_mul_f32_e32 v141, v1, v1
	v_fmac_f32_e32 v140, v2, v2
	v_fmac_f32_e32 v141, v3, v3
	v_fmac_f32_e32 v140, v4, v4
	v_fmac_f32_e32 v141, v5, v5
	v_fmac_f32_e32 v140, v6, v6
	v_fmac_f32_e32 v141, v7, v7
	v_fmac_f32_e32 v140, v8, v8
	v_fmac_f32_e32 v141, v9, v9
	v_fmac_f32_e32 v140, v10, v10
	v_fmac_f32_e32 v141, v11, v11
	v_fmac_f32_e32 v140, v12, v12
	v_fmac_f32_e32 v141, v13, v13
	v_fmac_f32_e32 v140, v14, v14
	v_fmac_f32_e32 v141, v15, v15
	v_fmac_f32_e32 v140, v16, v16
	v_fmac_f32_e32 v141, v17, v17
	v_fmac_f32_e32 v140, v18, v18
	v_fmac_f32_e32 v141, v19, v19
	v_fmac_f32_e32 v140, v20, v20
	v_fmac_f32_e32 v141, v21, v21
	v_fmac_f32_e32 v140, v22, v22
	v_fmac_f32_e32 v141, v23, v23
	v_fmac_f32_e32 v140, v24, v24
	v_fmac_f32_e32 v141, v25, v25
	v_fmac_f32_e32 v140, v26, v26
	v_fmac_f32_e32 v141, v27, v27
	v_fmac_f32_e32 v140, v28, v28
	v_fmac_f32_e32 v141, v29, v29
	v_fmac_f32_e32 v140, v30, v30
	v_fmac_f32_e32 v141, v31, v31
	v_add_f32_e32 v140, v140, v141
	s_nop 1
	v_add_f32_dpp v142, v140, v140 quad_perm:[1,0,3,2] row_mask:0xf bank_mask:0xf
	s_nop 1
	v_add_f32_dpp v142, v142, v142 quad_perm:[2,3,0,1] row_mask:0xf bank_mask:0xf
	s_nop 1
	v_add_f32_dpp v142, v142, v142 row_half_mirror row_mask:0xf bank_mask:0xf
	s_nop 1
	v_add_f32_dpp v142, v142, v142 row_mirror row_mask:0xf bank_mask:0xf
	s_nop 1
	v_readlane_b32 s20, v142, 0
	v_readlane_b32 s21, v142, 16
	v_readlane_b32 s22, v142, 32
	v_readlane_b32 s23, v142, 48
	s_nop 1
	v_mov_b32_e32 v143, s20
	v_add_f32_e32 v143, s21, v143
	v_add_f32_e32 v143, s22, v143
	v_add_f32_e32 v143, s23, v143
	v_fmamk_f32 v143, v143, 0x3a000000, v131
	v_rsq_f32_e32 v143, v143
	s_nop 0
	s_add_i32 s4, s6, 8
	s_lshl_b32 s5, s4, 12
	s_add_u32 s14, s84, s5
	s_addc_u32 s15, s85, 0
	s_add_u32 s14, s14, 0x11800000
	s_addc_u32 s15, s15, 0
	v_mul_f32_e32 v136, v143, v0
	v_mul_f32_e32 v137, v143, v1
	v_mul_f32_e32 v138, v143, v2
	v_mul_f32_e32 v139, v143, v3
	v_fma_f32 v136, v136, v64, v96
	v_fma_f32 v137, v137, v65, v97
	v_fma_f32 v138, v138, v66, v98
	v_fma_f32 v139, v139, v67, v99
	v_cvt_pk_bf16_f32 v132, v136, v137
	v_cvt_pk_bf16_f32 v133, v138, v139
	global_store_dwordx2 v130, v[132:133], s[14:15] offset:0
	v_mul_f32_e32 v136, v143, v4
	v_mul_f32_e32 v137, v143, v5
	v_mul_f32_e32 v138, v143, v6
	v_mul_f32_e32 v139, v143, v7
	v_fma_f32 v136, v136, v68, v100
	v_fma_f32 v137, v137, v69, v101
	v_fma_f32 v138, v138, v70, v102
	v_fma_f32 v139, v139, v71, v103
	v_cvt_pk_bf16_f32 v134, v136, v137
	v_cvt_pk_bf16_f32 v135, v138, v139
	global_store_dwordx2 v130, v[134:135], s[14:15] offset:512
	v_mul_f32_e32 v136, v143, v8
	v_mul_f32_e32 v137, v143, v9
	v_mul_f32_e32 v138, v143, v10
	v_mul_f32_e32 v139, v143, v11
	v_fma_f32 v136, v136, v72, v104
	v_fma_f32 v137, v137, v73, v105
	v_fma_f32 v138, v138, v74, v106
	v_fma_f32 v139, v139, v75, v107
	v_cvt_pk_bf16_f32 v132, v136, v137
	v_cvt_pk_bf16_f32 v133, v138, v139
	global_store_dwordx2 v130, v[132:133], s[14:15] offset:1024
	v_mul_f32_e32 v136, v143, v12
	v_mul_f32_e32 v137, v143, v13
	v_mul_f32_e32 v138, v143, v14
	v_mul_f32_e32 v139, v143, v15
	v_fma_f32 v136, v136, v76, v108
	v_fma_f32 v137, v137, v77, v109
	v_fma_f32 v138, v138, v78, v110
	v_fma_f32 v139, v139, v79, v111
	v_cvt_pk_bf16_f32 v134, v136, v137
	v_cvt_pk_bf16_f32 v135, v138, v139
	global_store_dwordx2 v130, v[134:135], s[14:15] offset:1536
	v_mul_f32_e32 v136, v143, v16
	v_mul_f32_e32 v137, v143, v17
	v_mul_f32_e32 v138, v143, v18
	v_mul_f32_e32 v139, v143, v19
	v_fma_f32 v136, v136, v80, v112
	v_fma_f32 v137, v137, v81, v113
	v_fma_f32 v138, v138, v82, v114
	v_fma_f32 v139, v139, v83, v115
	v_cvt_pk_bf16_f32 v132, v136, v137
	v_cvt_pk_bf16_f32 v133, v138, v139
	global_store_dwordx2 v130, v[132:133], s[14:15] offset:2048
	v_mul_f32_e32 v136, v143, v20
	v_mul_f32_e32 v137, v143, v21
	v_mul_f32_e32 v138, v143, v22
	v_mul_f32_e32 v139, v143, v23
	v_fma_f32 v136, v136, v84, v116
	v_fma_f32 v137, v137, v85, v117
	v_fma_f32 v138, v138, v86, v118
	v_fma_f32 v139, v139, v87, v119
	v_cvt_pk_bf16_f32 v134, v136, v137
	v_cvt_pk_bf16_f32 v135, v138, v139
	global_store_dwordx2 v130, v[134:135], s[14:15] offset:2560
	v_mul_f32_e32 v136, v143, v24
	v_mul_f32_e32 v137, v143, v25
	v_mul_f32_e32 v138, v143, v26
	v_mul_f32_e32 v139, v143, v27
	v_fma_f32 v136, v136, v88, v120
	v_fma_f32 v137, v137, v89, v121
	v_fma_f32 v138, v138, v90, v122
	v_fma_f32 v139, v139, v91, v123
	v_cvt_pk_bf16_f32 v132, v136, v137
	v_cvt_pk_bf16_f32 v133, v138, v139
	global_store_dwordx2 v130, v[132:133], s[14:15] offset:3072
	v_mul_f32_e32 v136, v143, v28
	v_mul_f32_e32 v137, v143, v29
	v_mul_f32_e32 v138, v143, v30
	v_mul_f32_e32 v139, v143, v31
	v_fma_f32 v136, v136, v92, v124
	v_fma_f32 v137, v137, v93, v125
	v_fma_f32 v138, v138, v94, v126
	v_fma_f32 v139, v139, v95, v127
	v_cvt_pk_bf16_f32 v134, v136, v137
	v_cvt_pk_bf16_f32 v135, v138, v139
	global_store_dwordx2 v130, v[134:135], s[14:15] offset:3584
	s_branch .LBB0_194

; __global__ void __launch_bounds__(NWAVES * 64, 2) mk_fwd(Args args) {
;     ...
;     if (IN(2)) {
;         pg8::Gemm g{H, WIN, MT, 4096, DM, DM, DM, 0}; pg8::StaticOrder S; S.init(MT, 4096, F.G, (int)blockIdx.x);
;         pg8::EpiPoolIn E{U, SG};
;         pg8::gemm_phase<pg8::EpiPoolIn>(F.lds, g, S, E);
.LBB0_244:
	s_cmpk_lg_i32 s63, 0x100
	s_cbranch_scc1 .Lh0reloc_skip
	s_add_u32 s12, s84, 0x11800000
	s_addc_u32 s13, s85, 0

; #define FRESH() int gtid; do { int t_ = threadIdx.x; asm volatile("" : "+v"(t_)); F.tid = t_; F.lane = t_ & 63; gtid = blockIdx.x * (NWAVES * 64) + t_; (void)gtid; } while (0)
; __global__ void __launch_bounds__(NWAVES * 64, 2) mk_fwd(Args args) {
;     ...
;     if (IN(3)) { FRESH();
;         for (int item = gtid; item < (MT / 8) * 256; item += NTHR) {
;             const int cc = item & 255, row0 = (item >> 8) * 8;
;             int base, L; if (row0 < ML) { base = row0 & ~(SEQ - 1); L = SEQ; } else { base = ML + ((row0 - ML) & ~(CTXL - 1)); L = CTXL; }
;             const int t0 = row0 - base, gidx = cc >> 6;
;             const bf16_t* Ub = U + (size_t)base * DM + cc * 8; bf16_t* Pb = P + (size_t)base * DM + cc * 8;
.LBB0_379:
	s_add_u32 s12, s84, 0x4000000
	s_addc_u32 s13, s85, 0
	s_cmp_lt_i32 s86, 4
	s_cselect_b64 s[0:1], -1, 0
	s_add_u32 s6, s84, 0x1a800000
	s_addc_u32 s7, s85, 0
	s_and_b64 s[4:5], s[0:1], s[4:5]
	s_andn2_b64 vcc, exec, s[4:5]
	s_cbranch_vccnz .LBB0_512
	v_mov_b32_e32 v0, v198
	s_mov_b32 s4, 0x90000
	v_lshl_add_u32 v130, s2, 9, v0
	v_cmp_gt_i32_e32 vcc, s4, v130
	s_and_saveexec_b64 s[4:5], vcc
	s_cbranch_execz .LBB0_511
	v_mov_b32_e32 v1, 4
	v_lshlrev_b32_sdwa v92, v1, v0 dst_sel:DWORD dst_unused:UNUSED_PAD src0_sel:DWORD src1_sel:BYTE_0
	v_mov_b32_e32 v93, 0
	v_bfe_u32 v131, v0, 6, 2
	v_lshl_add_u64 v[94:95], s[16:17], 0, v[92:93]
	v_lshl_add_u64 v[96:97], s[6:7], 0, v[92:93]
	s_mov_b64 s[8:9], 0
	s_movk_i32 s22, 0x4000
	v_mov_b32_e32 v132, 0x100
	v_mov_b32_e32 v133, 0x800
	v_mov_b32_e32 v134, 0xffffff00
	v_mov_b32_e32 v135, 0xfffff800
	s_mov_b32 s23, 0x8ffff
	s_branch .LBB0_385
